# v1 + sc1 (write-through) on the 48 P1 epilogue stores
# baseline (speedup 1.0000x reference)
; __device__ __forceinline__ unsigned cvt_pk_bf16(float lo, float hi) { unsigned r; asm volatile("v_cvt_pk_bf16_f32 %0, %1, %2" : "=v"(r) : "v"(lo), "v"(hi)); return r; }
; __device__ __forceinline__ float silu_f(float x) { return x * __builtin_amdgcn_rcpf(1.f + __expf(-x)); }
;     __device__ __forceinline__ void operator()(const f32x4 (&acc)[2][2][4][2], const pg8::Unit& u, int wr, int wc, int fr, int fq) const {
;     ...
;         } else {
;             const bool act = (sec == 3 || sec == 7);
;             const int col0 = 256 * half + 64 * wc + 8 * fq;
; #pragma unroll
;             for (int ai = 0; ai < 2; ++ai)
; #pragma unroll
;                 for (int m = 0; m < 4; ++m) {
;                     bf16_t* rowp = base + (size_t)(row0 + ai * 128 + m * 16) * 512 + col0;
; #pragma unroll
;                     for (int bj = 0; bj < 2; ++bj) { f32x4 v0 = acc[ai][bj][m][0], v1 = acc[ai][bj][m][1];
;                         if (act) { v0 = (f32x4){silu_f(v0[0]), silu_f(v0[1]), silu_f(v0[2]), silu_f(v0[3])}; v1 = (f32x4){silu_f(v1[0]), silu_f(v1[1]), silu_f(v1[2]), silu_f(v1[3])}; }
;                         u32x4 w; w.x = cvt_pk_bf16(v0[0], v0[1]); w.y = cvt_pk_bf16(v0[2], v0[3]); w.z = cvt_pk_bf16(v1[0], v1[1]); w.w = cvt_pk_bf16(v1[2], v1[3]);
;                         *(u32x4*)(rowp + 32 * bj) = w; }
;                 }
.LBB0_171:
	v_lshlrev_b32_e32 v130, 1, v182
	v_lshl_or_b32 v154, s27, 9, v130
	v_ashrrev_i32_e32 v173, 31, v172
	v_lshl_add_u64 v[130:131], s[48:49], 0, v[154:155]
	v_lshlrev_b64 v[132:133], 10, v[172:173]
	v_lshl_add_u64 v[132:133], v[130:131], 0, v[132:133]
	v_cvt_pk_bf16_f32 v138, v138, v139
	v_cvt_pk_bf16_f32 v139, v134, v135
	v_cvt_pk_bf16_f32 v140, v140, v141
	v_cvt_pk_bf16_f32 v141, v136, v137
	v_cndmask_b32_e64 v134, 0, 1, s[50:51]
	global_store_dwordx4 v[132:133], v[138:141], off sc1
	v_cmp_ne_u32_e64 s[4:5], 1, v134
	s_andn2_b64 vcc, exec, s[50:51]
	v_mov_b32_e32 v137, v117
	v_mov_b32_e32 v136, v116
	v_mov_b32_e32 v141, v115
	v_mov_b32_e32 v140, v114
	v_mov_b32_e32 v135, v121
	v_mov_b32_e32 v134, v120
	v_mov_b32_e32 v139, v119
	v_mov_b32_e32 v138, v118
	s_cbranch_vccnz .LBB0_173
	v_mul_f32_e32 v134, 0xbfb8aa3b, v118
	v_exp_f32_e32 v134, v134
	v_mul_f32_e32 v135, 0xbfb8aa3b, v119
	v_mul_f32_e32 v136, 0xbfb8aa3b, v120
	v_exp_f32_e32 v135, v135
	v_exp_f32_e32 v138, v136
	v_add_f32_e32 v134, 1.0, v134
	v_rcp_f32_e32 v136, v134
	v_add_f32_e32 v134, 1.0, v135
	v_rcp_f32_e32 v137, v134
	v_add_f32_e32 v134, 1.0, v138
	v_mul_f32_e32 v138, 0xbfb8aa3b, v114
	v_exp_f32_e32 v138, v138
	v_mul_f32_e32 v139, 0xbfb8aa3b, v116
	v_mul_f32_e32 v135, 0xbfb8aa3b, v121
	v_exp_f32_e32 v139, v139
	v_add_f32_e32 v138, 1.0, v138
	v_rcp_f32_e32 v140, v138
	v_mul_f32_e32 v138, 0xbfb8aa3b, v115
	v_mul_f32_e32 v141, 0xbfb8aa3b, v117
	v_exp_f32_e32 v135, v135
	v_exp_f32_e32 v138, v138
	v_exp_f32_e32 v141, v141
	v_add_f32_e32 v139, 1.0, v139
	v_add_f32_e32 v135, 1.0, v135
	v_add_f32_e32 v138, 1.0, v138
	v_rcp_f32_e32 v142, v139
	v_add_f32_e32 v139, 1.0, v141
	v_rcp_f32_e32 v134, v134
	v_rcp_f32_e32 v135, v135
	v_rcp_f32_e32 v143, v139
	v_rcp_f32_e32 v141, v138
	v_pk_mul_f32 v[138:139], v[118:119], v[136:137]
	v_pk_mul_f32 v[134:135], v[120:121], v[134:135]
	v_pk_mul_f32 v[136:137], v[116:117], v[142:143]
	v_pk_mul_f32 v[140:141], v[114:115], v[140:141]
.LBB0_173:
	v_cvt_pk_bf16_f32 v138, v138, v139
	v_cvt_pk_bf16_f32 v139, v134, v135
	s_nop 0
	v_cvt_pk_bf16_f32 v140, v140, v141
	v_cvt_pk_bf16_f32 v141, v136, v137
	global_store_dwordx4 v[132:133], v[138:141], off offset:64 sc1
	s_and_b64 vcc, exec, s[4:5]
	v_mov_b32_e32 v137, v109
	v_mov_b32_e32 v136, v108
	v_mov_b32_e32 v141, v107
	v_mov_b32_e32 v140, v106
	v_mov_b32_e32 v135, v113
	v_mov_b32_e32 v134, v112
	v_mov_b32_e32 v139, v111
	v_mov_b32_e32 v138, v110
	s_cbranch_vccnz .LBB0_175
	v_mul_f32_e32 v136, 0xbfb8aa3b, v106
	v_exp_f32_e32 v136, v136
	v_mul_f32_e32 v132, 0xbfb8aa3b, v110
	v_mul_f32_e32 v133, 0xbfb8aa3b, v111
	v_mul_f32_e32 v134, 0xbfb8aa3b, v112
	v_add_f32_e32 v136, 1.0, v136
	v_mul_f32_e32 v135, 0xbfb8aa3b, v113
	v_rcp_f32_e32 v140, v136
	v_mul_f32_e32 v136, 0xbfb8aa3b, v107
	v_mul_f32_e32 v137, 0xbfb8aa3b, v108
	v_mul_f32_e32 v138, 0xbfb8aa3b, v109
	v_exp_f32_e32 v132, v132
	v_exp_f32_e32 v133, v133
	v_exp_f32_e32 v134, v134
	v_exp_f32_e32 v135, v135
	v_exp_f32_e32 v136, v136
	v_exp_f32_e32 v137, v137
	v_exp_f32_e32 v138, v138
	v_add_f32_e32 v132, 1.0, v132
	v_add_f32_e32 v133, 1.0, v133
	v_add_f32_e32 v134, 1.0, v134
	v_add_f32_e32 v135, 1.0, v135
	v_add_f32_e32 v139, 1.0, v136
	v_add_f32_e32 v136, 1.0, v137
	v_add_f32_e32 v137, 1.0, v138
	v_rcp_f32_e32 v132, v132
	v_rcp_f32_e32 v133, v133
	v_rcp_f32_e32 v134, v134
	v_rcp_f32_e32 v135, v135
	v_rcp_f32_e32 v136, v136
	v_rcp_f32_e32 v137, v137
	v_rcp_f32_e32 v141, v139
	v_pk_mul_f32 v[134:135], v[112:113], v[134:135]
	v_pk_mul_f32 v[138:139], v[110:111], v[132:133]
	v_pk_mul_f32 v[136:137], v[108:109], v[136:137]
	v_pk_mul_f32 v[140:141], v[106:107], v[140:141]
.LBB0_175:
	v_or_b32_e32 v132, 16, v172
	v_ashrrev_i32_e32 v133, 31, v132
	v_lshlrev_b64 v[132:133], 10, v[132:133]
	v_lshl_add_u64 v[132:133], v[130:131], 0, v[132:133]
	v_cvt_pk_bf16_f32 v138, v138, v139
	v_cvt_pk_bf16_f32 v139, v134, v135
	v_cvt_pk_bf16_f32 v140, v140, v141
	v_cvt_pk_bf16_f32 v141, v136, v137
	global_store_dwordx4 v[132:133], v[138:141], off sc1
	s_and_b64 vcc, exec, s[4:5]
	v_mov_b32_e32 v137, v101
	v_mov_b32_e32 v136, v100
	v_mov_b32_e32 v141, v99
	v_mov_b32_e32 v140, v98
	v_mov_b32_e32 v135, v105
	v_mov_b32_e32 v134, v104
	v_mov_b32_e32 v139, v103
	v_mov_b32_e32 v138, v102
	s_cbranch_vccnz .LBB0_177
	v_mul_f32_e32 v134, 0xbfb8aa3b, v102
	v_exp_f32_e32 v134, v134
	v_mul_f32_e32 v135, 0xbfb8aa3b, v103
	v_mul_f32_e32 v136, 0xbfb8aa3b, v104
	v_exp_f32_e32 v135, v135
	v_exp_f32_e32 v138, v136
	v_add_f32_e32 v134, 1.0, v134
	v_rcp_f32_e32 v136, v134
	v_add_f32_e32 v134, 1.0, v135
	v_rcp_f32_e32 v137, v134
	v_add_f32_e32 v134, 1.0, v138
	v_mul_f32_e32 v138, 0xbfb8aa3b, v98
	v_exp_f32_e32 v138, v138
	v_mul_f32_e32 v139, 0xbfb8aa3b, v100
	v_mul_f32_e32 v135, 0xbfb8aa3b, v105
	v_exp_f32_e32 v139, v139
	v_add_f32_e32 v138, 1.0, v138
	v_rcp_f32_e32 v140, v138
	v_mul_f32_e32 v138, 0xbfb8aa3b, v99
	v_mul_f32_e32 v141, 0xbfb8aa3b, v101
	v_exp_f32_e32 v135, v135
	v_exp_f32_e32 v138, v138
	v_exp_f32_e32 v141, v141
	v_add_f32_e32 v139, 1.0, v139
	v_add_f32_e32 v135, 1.0, v135
	v_add_f32_e32 v138, 1.0, v138
	v_rcp_f32_e32 v142, v139
	v_add_f32_e32 v139, 1.0, v141
	v_rcp_f32_e32 v134, v134
	v_rcp_f32_e32 v135, v135
	v_rcp_f32_e32 v143, v139
	v_rcp_f32_e32 v141, v138
	v_pk_mul_f32 v[138:139], v[102:103], v[136:137]
	v_pk_mul_f32 v[134:135], v[104:105], v[134:135]
	v_pk_mul_f32 v[136:137], v[100:101], v[142:143]
	v_pk_mul_f32 v[140:141], v[98:99], v[140:141]
; __device__ __forceinline__ unsigned cvt_pk_bf16(float lo, float hi) { unsigned r; asm volatile("v_cvt_pk_bf16_f32 %0, %1, %2" : "=v"(r) : "v"(lo), "v"(hi)); return r; }
; __device__ __forceinline__ float silu_f(float x) { return x * __builtin_amdgcn_rcpf(1.f + __expf(-x)); }
;     __device__ __forceinline__ void operator()(const f32x4 (&acc)[2][2][4][2], const pg8::Unit& u, int wr, int wc, int fr, int fq) const {
;     ...
; #pragma unroll
;             for (int ai = 0; ai < 2; ++ai)
; #pragma unroll
;                 for (int m = 0; m < 4; ++m) {
;                     bf16_t* rowp = base + (size_t)(row0 + ai * 128 + m * 16) * 512 + col0;
; #pragma unroll
;                     for (int bj = 0; bj < 2; ++bj) { f32x4 v0 = acc[ai][bj][m][0], v1 = acc[ai][bj][m][1];
;                         if (act) { v0 = (f32x4){silu_f(v0[0]), silu_f(v0[1]), silu_f(v0[2]), silu_f(v0[3])}; v1 = (f32x4){silu_f(v1[0]), silu_f(v1[1]), silu_f(v1[2]), silu_f(v1[3])}; }
;                         u32x4 w; w.x = cvt_pk_bf16(v0[0], v0[1]); w.y = cvt_pk_bf16(v0[2], v0[3]); w.z = cvt_pk_bf16(v1[0], v1[1]); w.w = cvt_pk_bf16(v1[2], v1[3]);
;                         *(u32x4*)(rowp + 32 * bj) = w; }
;                 }
.LBB0_177:
	v_cvt_pk_bf16_f32 v138, v138, v139
	v_cvt_pk_bf16_f32 v139, v134, v135
	s_nop 0
	v_cvt_pk_bf16_f32 v140, v140, v141
	v_cvt_pk_bf16_f32 v141, v136, v137
	global_store_dwordx4 v[132:133], v[138:141], off offset:64 sc1
	s_and_b64 vcc, exec, s[4:5]
	v_mov_b32_e32 v137, v93
	v_mov_b32_e32 v136, v92
	v_mov_b32_e32 v141, v91
	v_mov_b32_e32 v140, v90
	v_mov_b32_e32 v135, v97
	v_mov_b32_e32 v134, v96
	v_mov_b32_e32 v139, v95
	v_mov_b32_e32 v138, v94
	s_cbranch_vccnz .LBB0_179
	v_mul_f32_e32 v136, 0xbfb8aa3b, v90
	v_exp_f32_e32 v136, v136
	v_mul_f32_e32 v132, 0xbfb8aa3b, v94
	v_mul_f32_e32 v133, 0xbfb8aa3b, v95
	v_mul_f32_e32 v134, 0xbfb8aa3b, v96
	v_add_f32_e32 v136, 1.0, v136
	v_mul_f32_e32 v135, 0xbfb8aa3b, v97
	v_rcp_f32_e32 v140, v136
	v_mul_f32_e32 v136, 0xbfb8aa3b, v91
	v_mul_f32_e32 v137, 0xbfb8aa3b, v92
	v_mul_f32_e32 v138, 0xbfb8aa3b, v93
	v_exp_f32_e32 v132, v132
	v_exp_f32_e32 v133, v133
	v_exp_f32_e32 v134, v134
	v_exp_f32_e32 v135, v135
	v_exp_f32_e32 v136, v136
	v_exp_f32_e32 v137, v137
	v_exp_f32_e32 v138, v138
	v_add_f32_e32 v132, 1.0, v132
	v_add_f32_e32 v133, 1.0, v133
	v_add_f32_e32 v134, 1.0, v134
	v_add_f32_e32 v135, 1.0, v135
	v_add_f32_e32 v139, 1.0, v136
	v_add_f32_e32 v136, 1.0, v137
	v_add_f32_e32 v137, 1.0, v138
	v_rcp_f32_e32 v132, v132
	v_rcp_f32_e32 v133, v133
	v_rcp_f32_e32 v134, v134
	v_rcp_f32_e32 v135, v135
	v_rcp_f32_e32 v136, v136
	v_rcp_f32_e32 v137, v137
	v_rcp_f32_e32 v141, v139
	v_pk_mul_f32 v[134:135], v[96:97], v[134:135]
	v_pk_mul_f32 v[138:139], v[94:95], v[132:133]
	v_pk_mul_f32 v[136:137], v[92:93], v[136:137]
	v_pk_mul_f32 v[140:141], v[90:91], v[140:141]
.LBB0_179:
	v_or_b32_e32 v132, 32, v172
	v_ashrrev_i32_e32 v133, 31, v132
	v_lshlrev_b64 v[132:133], 10, v[132:133]
	v_lshl_add_u64 v[132:133], v[130:131], 0, v[132:133]
	v_cvt_pk_bf16_f32 v138, v138, v139
	v_cvt_pk_bf16_f32 v139, v134, v135
	v_cvt_pk_bf16_f32 v140, v140, v141
	v_cvt_pk_bf16_f32 v141, v136, v137
	global_store_dwordx4 v[132:133], v[138:141], off sc1
	s_and_b64 vcc, exec, s[4:5]
	v_mov_b32_e32 v137, v85
	v_mov_b32_e32 v136, v84
	v_mov_b32_e32 v141, v83
	v_mov_b32_e32 v140, v82
	v_mov_b32_e32 v135, v89
	v_mov_b32_e32 v134, v88
	v_mov_b32_e32 v139, v87
	v_mov_b32_e32 v138, v86
	s_cbranch_vccnz .LBB0_181
	v_mul_f32_e32 v134, 0xbfb8aa3b, v86
	v_exp_f32_e32 v134, v134
	v_mul_f32_e32 v135, 0xbfb8aa3b, v87
	v_mul_f32_e32 v136, 0xbfb8aa3b, v88
	v_exp_f32_e32 v135, v135
	v_exp_f32_e32 v138, v136
	v_add_f32_e32 v134, 1.0, v134
	v_rcp_f32_e32 v136, v134
	v_add_f32_e32 v134, 1.0, v135
	v_rcp_f32_e32 v137, v134
	v_add_f32_e32 v134, 1.0, v138
	v_mul_f32_e32 v138, 0xbfb8aa3b, v82
	v_exp_f32_e32 v138, v138
	v_mul_f32_e32 v139, 0xbfb8aa3b, v84
	v_mul_f32_e32 v135, 0xbfb8aa3b, v89
	v_exp_f32_e32 v139, v139
	v_add_f32_e32 v138, 1.0, v138
	v_rcp_f32_e32 v140, v138
	v_mul_f32_e32 v138, 0xbfb8aa3b, v83
	v_mul_f32_e32 v141, 0xbfb8aa3b, v85
	v_exp_f32_e32 v135, v135
	v_exp_f32_e32 v138, v138
	v_exp_f32_e32 v141, v141
	v_add_f32_e32 v139, 1.0, v139
	v_add_f32_e32 v135, 1.0, v135
	v_add_f32_e32 v138, 1.0, v138
	v_rcp_f32_e32 v142, v139
	v_add_f32_e32 v139, 1.0, v141
	v_rcp_f32_e32 v134, v134
	v_rcp_f32_e32 v135, v135
	v_rcp_f32_e32 v143, v139
	v_rcp_f32_e32 v141, v138
	v_pk_mul_f32 v[138:139], v[86:87], v[136:137]
	v_pk_mul_f32 v[134:135], v[88:89], v[134:135]
	v_pk_mul_f32 v[136:137], v[84:85], v[142:143]
	v_pk_mul_f32 v[140:141], v[82:83], v[140:141]
.LBB0_181:
	v_cvt_pk_bf16_f32 v138, v138, v139
	v_cvt_pk_bf16_f32 v139, v134, v135
	s_nop 0
	v_cvt_pk_bf16_f32 v140, v140, v141
	v_cvt_pk_bf16_f32 v141, v136, v137
	global_store_dwordx4 v[132:133], v[138:141], off offset:64 sc1
	s_and_b64 vcc, exec, s[4:5]
	v_mov_b32_e32 v137, v77
	v_mov_b32_e32 v136, v76
	v_mov_b32_e32 v141, v75
	v_mov_b32_e32 v140, v74
	v_mov_b32_e32 v135, v81
	v_mov_b32_e32 v134, v80
	v_mov_b32_e32 v139, v79
	v_mov_b32_e32 v138, v78
	s_cbranch_vccnz .LBB0_183
	v_mul_f32_e32 v136, 0xbfb8aa3b, v74
	v_exp_f32_e32 v136, v136
	v_mul_f32_e32 v132, 0xbfb8aa3b, v78
	v_mul_f32_e32 v133, 0xbfb8aa3b, v79
	v_mul_f32_e32 v134, 0xbfb8aa3b, v80
	v_add_f32_e32 v136, 1.0, v136
	v_mul_f32_e32 v135, 0xbfb8aa3b, v81
	v_rcp_f32_e32 v140, v136
	v_mul_f32_e32 v136, 0xbfb8aa3b, v75
	v_mul_f32_e32 v137, 0xbfb8aa3b, v76
	v_mul_f32_e32 v138, 0xbfb8aa3b, v77
	v_exp_f32_e32 v132, v132
	v_exp_f32_e32 v133, v133
	v_exp_f32_e32 v134, v134
	v_exp_f32_e32 v135, v135
	v_exp_f32_e32 v136, v136
	v_exp_f32_e32 v137, v137
	v_exp_f32_e32 v138, v138
	v_add_f32_e32 v132, 1.0, v132
	v_add_f32_e32 v133, 1.0, v133
	v_add_f32_e32 v134, 1.0, v134
	v_add_f32_e32 v135, 1.0, v135
	v_add_f32_e32 v139, 1.0, v136
	v_add_f32_e32 v136, 1.0, v137
	v_add_f32_e32 v137, 1.0, v138
	v_rcp_f32_e32 v132, v132
	v_rcp_f32_e32 v133, v133
	v_rcp_f32_e32 v134, v134
	v_rcp_f32_e32 v135, v135
	v_rcp_f32_e32 v136, v136
	v_rcp_f32_e32 v137, v137
	v_rcp_f32_e32 v141, v139
	v_pk_mul_f32 v[134:135], v[80:81], v[134:135]
	v_pk_mul_f32 v[138:139], v[78:79], v[132:133]
	v_pk_mul_f32 v[136:137], v[76:77], v[136:137]
	v_pk_mul_f32 v[140:141], v[74:75], v[140:141]
; __device__ __forceinline__ unsigned cvt_pk_bf16(float lo, float hi) { unsigned r; asm volatile("v_cvt_pk_bf16_f32 %0, %1, %2" : "=v"(r) : "v"(lo), "v"(hi)); return r; }
; __device__ __forceinline__ float silu_f(float x) { return x * __builtin_amdgcn_rcpf(1.f + __expf(-x)); }
;     __device__ __forceinline__ void operator()(const f32x4 (&acc)[2][2][4][2], const pg8::Unit& u, int wr, int wc, int fr, int fq) const {
;     ...
; #pragma unroll
;             for (int ai = 0; ai < 2; ++ai)
; #pragma unroll
;                 for (int m = 0; m < 4; ++m) {
;                     bf16_t* rowp = base + (size_t)(row0 + ai * 128 + m * 16) * 512 + col0;
; #pragma unroll
;                     for (int bj = 0; bj < 2; ++bj) { f32x4 v0 = acc[ai][bj][m][0], v1 = acc[ai][bj][m][1];
;                         if (act) { v0 = (f32x4){silu_f(v0[0]), silu_f(v0[1]), silu_f(v0[2]), silu_f(v0[3])}; v1 = (f32x4){silu_f(v1[0]), silu_f(v1[1]), silu_f(v1[2]), silu_f(v1[3])}; }
;                         u32x4 w; w.x = cvt_pk_bf16(v0[0], v0[1]); w.y = cvt_pk_bf16(v0[2], v0[3]); w.z = cvt_pk_bf16(v1[0], v1[1]); w.w = cvt_pk_bf16(v1[2], v1[3]);
;                         *(u32x4*)(rowp + 32 * bj) = w; }
;                 }
.LBB0_183:
	v_or_b32_e32 v132, 48, v172
	v_ashrrev_i32_e32 v133, 31, v132
	v_lshlrev_b64 v[132:133], 10, v[132:133]
	v_lshl_add_u64 v[132:133], v[130:131], 0, v[132:133]
	v_cvt_pk_bf16_f32 v138, v138, v139
	v_cvt_pk_bf16_f32 v139, v134, v135
	v_cvt_pk_bf16_f32 v140, v140, v141
	v_cvt_pk_bf16_f32 v141, v136, v137
	global_store_dwordx4 v[132:133], v[138:141], off sc1
	s_and_b64 vcc, exec, s[4:5]
	v_mov_b32_e32 v137, v69
	v_mov_b32_e32 v136, v68
	v_mov_b32_e32 v141, v67
	v_mov_b32_e32 v140, v66
	v_mov_b32_e32 v135, v73
	v_mov_b32_e32 v134, v72
	v_mov_b32_e32 v139, v71
	v_mov_b32_e32 v138, v70
	s_cbranch_vccnz .LBB0_185
	v_mul_f32_e32 v134, 0xbfb8aa3b, v70
	v_exp_f32_e32 v134, v134
	v_mul_f32_e32 v135, 0xbfb8aa3b, v71
	v_mul_f32_e32 v136, 0xbfb8aa3b, v72
	v_exp_f32_e32 v135, v135
	v_exp_f32_e32 v138, v136
	v_add_f32_e32 v134, 1.0, v134
	v_rcp_f32_e32 v136, v134
	v_add_f32_e32 v134, 1.0, v135
	v_rcp_f32_e32 v137, v134
	v_add_f32_e32 v134, 1.0, v138
	v_mul_f32_e32 v138, 0xbfb8aa3b, v66
	v_exp_f32_e32 v138, v138
	v_mul_f32_e32 v139, 0xbfb8aa3b, v68
	v_mul_f32_e32 v135, 0xbfb8aa3b, v73
	v_exp_f32_e32 v139, v139
	v_add_f32_e32 v138, 1.0, v138
	v_rcp_f32_e32 v140, v138
	v_mul_f32_e32 v138, 0xbfb8aa3b, v67
	v_mul_f32_e32 v141, 0xbfb8aa3b, v69
	v_exp_f32_e32 v135, v135
	v_exp_f32_e32 v138, v138
	v_exp_f32_e32 v141, v141
	v_add_f32_e32 v139, 1.0, v139
	v_add_f32_e32 v135, 1.0, v135
	v_add_f32_e32 v138, 1.0, v138
	v_rcp_f32_e32 v142, v139
	v_add_f32_e32 v139, 1.0, v141
	v_rcp_f32_e32 v134, v134
	v_rcp_f32_e32 v135, v135
	v_rcp_f32_e32 v143, v139
	v_rcp_f32_e32 v141, v138
	v_pk_mul_f32 v[138:139], v[70:71], v[136:137]
	v_pk_mul_f32 v[134:135], v[72:73], v[134:135]
	v_pk_mul_f32 v[136:137], v[68:69], v[142:143]
	v_pk_mul_f32 v[140:141], v[66:67], v[140:141]
.LBB0_185:
	v_cvt_pk_bf16_f32 v138, v138, v139
	v_cvt_pk_bf16_f32 v139, v134, v135
	s_nop 0
	v_cvt_pk_bf16_f32 v140, v140, v141
	v_cvt_pk_bf16_f32 v141, v136, v137
	global_store_dwordx4 v[132:133], v[138:141], off offset:64 sc1
	s_and_b64 vcc, exec, s[4:5]
	v_mov_b32_e32 v137, v61
	v_mov_b32_e32 v136, v60
	v_mov_b32_e32 v141, v59
	v_mov_b32_e32 v140, v58
	v_mov_b32_e32 v135, v65
	v_mov_b32_e32 v134, v64
	v_mov_b32_e32 v139, v63
	v_mov_b32_e32 v138, v62
	s_cbranch_vccnz .LBB0_187
	v_mul_f32_e32 v136, 0xbfb8aa3b, v58
	v_exp_f32_e32 v136, v136
	v_mul_f32_e32 v132, 0xbfb8aa3b, v62
	v_mul_f32_e32 v133, 0xbfb8aa3b, v63
	v_mul_f32_e32 v134, 0xbfb8aa3b, v64
	v_add_f32_e32 v136, 1.0, v136
	v_mul_f32_e32 v135, 0xbfb8aa3b, v65
	v_rcp_f32_e32 v140, v136
	v_mul_f32_e32 v136, 0xbfb8aa3b, v59
	v_mul_f32_e32 v137, 0xbfb8aa3b, v60
	v_mul_f32_e32 v138, 0xbfb8aa3b, v61
	v_exp_f32_e32 v132, v132
	v_exp_f32_e32 v133, v133
	v_exp_f32_e32 v134, v134
	v_exp_f32_e32 v135, v135
	v_exp_f32_e32 v136, v136
	v_exp_f32_e32 v137, v137
	v_exp_f32_e32 v138, v138
	v_add_f32_e32 v132, 1.0, v132
	v_add_f32_e32 v133, 1.0, v133
	v_add_f32_e32 v134, 1.0, v134
	v_add_f32_e32 v135, 1.0, v135
	v_add_f32_e32 v139, 1.0, v136
	v_add_f32_e32 v136, 1.0, v137
	v_add_f32_e32 v137, 1.0, v138
	v_rcp_f32_e32 v132, v132
	v_rcp_f32_e32 v133, v133
	v_rcp_f32_e32 v134, v134
	v_rcp_f32_e32 v135, v135
	v_rcp_f32_e32 v136, v136
	v_rcp_f32_e32 v137, v137
	v_rcp_f32_e32 v141, v139
	v_pk_mul_f32 v[134:135], v[64:65], v[134:135]
	v_pk_mul_f32 v[138:139], v[62:63], v[132:133]
	v_pk_mul_f32 v[136:137], v[60:61], v[136:137]
	v_pk_mul_f32 v[140:141], v[58:59], v[140:141]
.LBB0_187:
	v_lshlrev_b64 v[132:133], 10, v[172:173]
	v_lshl_add_u64 v[132:133], v[130:131], 0, v[132:133]
	v_cvt_pk_bf16_f32 v138, v138, v139
	v_cvt_pk_bf16_f32 v139, v134, v135
	v_add_co_u32_e32 v134, vcc, 0x20000, v132
	v_cvt_pk_bf16_f32 v140, v140, v141
	v_cvt_pk_bf16_f32 v141, v136, v137
	v_mov_b32_e32 v137, v53
	s_nop 0
	v_addc_co_u32_e32 v135, vcc, 0, v133, vcc
	global_store_dwordx4 v[134:135], v[138:141], off sc1
	s_and_b64 vcc, exec, s[4:5]
	v_mov_b32_e32 v136, v52
	v_mov_b32_e32 v141, v51
	v_mov_b32_e32 v140, v50
	v_mov_b32_e32 v135, v57
	v_mov_b32_e32 v134, v56
	v_mov_b32_e32 v139, v55
	v_mov_b32_e32 v138, v54
	s_cbranch_vccnz .LBB0_189
	v_mul_f32_e32 v134, 0xbfb8aa3b, v54
	v_exp_f32_e32 v134, v134
	v_mul_f32_e32 v135, 0xbfb8aa3b, v55
	v_mul_f32_e32 v136, 0xbfb8aa3b, v56
	v_exp_f32_e32 v135, v135
	v_exp_f32_e32 v138, v136
	v_add_f32_e32 v134, 1.0, v134
	v_rcp_f32_e32 v136, v134
	v_add_f32_e32 v134, 1.0, v135
	v_rcp_f32_e32 v137, v134
	v_add_f32_e32 v134, 1.0, v138
	v_mul_f32_e32 v138, 0xbfb8aa3b, v50
	v_exp_f32_e32 v138, v138
	v_mul_f32_e32 v139, 0xbfb8aa3b, v52
	v_mul_f32_e32 v135, 0xbfb8aa3b, v57
	v_exp_f32_e32 v139, v139
	v_add_f32_e32 v138, 1.0, v138
	v_rcp_f32_e32 v140, v138
	v_mul_f32_e32 v138, 0xbfb8aa3b, v51
	v_mul_f32_e32 v141, 0xbfb8aa3b, v53
	v_exp_f32_e32 v135, v135
	v_exp_f32_e32 v138, v138
	v_exp_f32_e32 v141, v141
	v_add_f32_e32 v139, 1.0, v139
	v_add_f32_e32 v135, 1.0, v135
	v_add_f32_e32 v138, 1.0, v138
	v_rcp_f32_e32 v142, v139
	v_add_f32_e32 v139, 1.0, v141
	v_rcp_f32_e32 v134, v134
	v_rcp_f32_e32 v135, v135
	v_rcp_f32_e32 v143, v139
	v_rcp_f32_e32 v141, v138
	v_pk_mul_f32 v[138:139], v[54:55], v[136:137]
	v_pk_mul_f32 v[134:135], v[56:57], v[134:135]
	v_pk_mul_f32 v[136:137], v[52:53], v[142:143]
	v_pk_mul_f32 v[140:141], v[50:51], v[140:141]
; __device__ __forceinline__ unsigned cvt_pk_bf16(float lo, float hi) { unsigned r; asm volatile("v_cvt_pk_bf16_f32 %0, %1, %2" : "=v"(r) : "v"(lo), "v"(hi)); return r; }
; __device__ __forceinline__ float silu_f(float x) { return x * __builtin_amdgcn_rcpf(1.f + __expf(-x)); }
;     __device__ __forceinline__ void operator()(const f32x4 (&acc)[2][2][4][2], const pg8::Unit& u, int wr, int wc, int fr, int fq) const {
;     ...
; #pragma unroll
;             for (int ai = 0; ai < 2; ++ai)
; #pragma unroll
;                 for (int m = 0; m < 4; ++m) {
;                     bf16_t* rowp = base + (size_t)(row0 + ai * 128 + m * 16) * 512 + col0;
; #pragma unroll
;                     for (int bj = 0; bj < 2; ++bj) { f32x4 v0 = acc[ai][bj][m][0], v1 = acc[ai][bj][m][1];
;                         if (act) { v0 = (f32x4){silu_f(v0[0]), silu_f(v0[1]), silu_f(v0[2]), silu_f(v0[3])}; v1 = (f32x4){silu_f(v1[0]), silu_f(v1[1]), silu_f(v1[2]), silu_f(v1[3])}; }
;                         u32x4 w; w.x = cvt_pk_bf16(v0[0], v0[1]); w.y = cvt_pk_bf16(v0[2], v0[3]); w.z = cvt_pk_bf16(v1[0], v1[1]); w.w = cvt_pk_bf16(v1[2], v1[3]);
;                         *(u32x4*)(rowp + 32 * bj) = w; }
;                 }
.LBB0_189:
	v_lshl_add_u64 v[142:143], v[132:133], 0, s[16:17]
	v_cvt_pk_bf16_f32 v132, v138, v139
	v_cvt_pk_bf16_f32 v133, v134, v135
	v_cvt_pk_bf16_f32 v134, v140, v141
	v_cvt_pk_bf16_f32 v135, v136, v137
	global_store_dwordx4 v[142:143], v[132:135], off offset:64 sc1
	s_and_b64 vcc, exec, s[4:5]
	v_mov_b32_e32 v137, v45
	v_mov_b32_e32 v136, v44
	v_mov_b32_e32 v141, v43
	v_mov_b32_e32 v140, v42
	v_mov_b32_e32 v135, v49
	v_mov_b32_e32 v134, v48
	v_mov_b32_e32 v139, v47
	v_mov_b32_e32 v138, v46
	s_cbranch_vccnz .LBB0_191
	v_mul_f32_e32 v136, 0xbfb8aa3b, v42
	v_exp_f32_e32 v136, v136
	v_mul_f32_e32 v132, 0xbfb8aa3b, v46
	v_mul_f32_e32 v133, 0xbfb8aa3b, v47
	v_mul_f32_e32 v134, 0xbfb8aa3b, v48
	v_add_f32_e32 v136, 1.0, v136
	v_mul_f32_e32 v135, 0xbfb8aa3b, v49
	v_rcp_f32_e32 v140, v136
	v_mul_f32_e32 v136, 0xbfb8aa3b, v43
	v_mul_f32_e32 v137, 0xbfb8aa3b, v44
	v_mul_f32_e32 v138, 0xbfb8aa3b, v45
	v_exp_f32_e32 v132, v132
	v_exp_f32_e32 v133, v133
	v_exp_f32_e32 v134, v134
	v_exp_f32_e32 v135, v135
	v_exp_f32_e32 v136, v136
	v_exp_f32_e32 v137, v137
	v_exp_f32_e32 v138, v138
	v_add_f32_e32 v132, 1.0, v132
	v_add_f32_e32 v133, 1.0, v133
	v_add_f32_e32 v134, 1.0, v134
	v_add_f32_e32 v135, 1.0, v135
	v_add_f32_e32 v139, 1.0, v136
	v_add_f32_e32 v136, 1.0, v137
	v_add_f32_e32 v137, 1.0, v138
	v_rcp_f32_e32 v132, v132
	v_rcp_f32_e32 v133, v133
	v_rcp_f32_e32 v134, v134
	v_rcp_f32_e32 v135, v135
	v_rcp_f32_e32 v136, v136
	v_rcp_f32_e32 v137, v137
	v_rcp_f32_e32 v141, v139
	v_pk_mul_f32 v[134:135], v[48:49], v[134:135]
	v_pk_mul_f32 v[138:139], v[46:47], v[132:133]
	v_pk_mul_f32 v[136:137], v[44:45], v[136:137]
	v_pk_mul_f32 v[140:141], v[42:43], v[140:141]
.LBB0_191:
	v_lshlrev_b64 v[132:133], 10, v[172:173]
	v_lshl_add_u64 v[132:133], v[130:131], 0, v[132:133]
	v_cvt_pk_bf16_f32 v138, v138, v139
	v_cvt_pk_bf16_f32 v139, v134, v135
	v_add_co_u32_e32 v134, vcc, 0x24000, v132
	v_cvt_pk_bf16_f32 v140, v140, v141
	v_cvt_pk_bf16_f32 v141, v136, v137
	v_mov_b32_e32 v137, v37
	s_nop 0
	v_addc_co_u32_e32 v135, vcc, 0, v133, vcc
	global_store_dwordx4 v[134:135], v[138:141], off sc1
	s_and_b64 vcc, exec, s[4:5]
	v_mov_b32_e32 v136, v36
	v_mov_b32_e32 v141, v35
	v_mov_b32_e32 v140, v34
	v_mov_b32_e32 v135, v41
	v_mov_b32_e32 v134, v40
	v_mov_b32_e32 v139, v39
	v_mov_b32_e32 v138, v38
	s_cbranch_vccnz .LBB0_193
	v_mul_f32_e32 v134, 0xbfb8aa3b, v38
	v_exp_f32_e32 v134, v134
	v_mul_f32_e32 v135, 0xbfb8aa3b, v39
	v_mul_f32_e32 v136, 0xbfb8aa3b, v40
	v_exp_f32_e32 v135, v135
	v_exp_f32_e32 v138, v136
	v_add_f32_e32 v134, 1.0, v134
	v_rcp_f32_e32 v136, v134
	v_add_f32_e32 v134, 1.0, v135
	v_rcp_f32_e32 v137, v134
	v_add_f32_e32 v134, 1.0, v138
	v_mul_f32_e32 v138, 0xbfb8aa3b, v34
	v_exp_f32_e32 v138, v138
	v_mul_f32_e32 v139, 0xbfb8aa3b, v36
	v_mul_f32_e32 v135, 0xbfb8aa3b, v41
	v_exp_f32_e32 v139, v139
	v_add_f32_e32 v138, 1.0, v138
	v_rcp_f32_e32 v140, v138
	v_mul_f32_e32 v138, 0xbfb8aa3b, v35
	v_mul_f32_e32 v141, 0xbfb8aa3b, v37
	v_exp_f32_e32 v135, v135
	v_exp_f32_e32 v138, v138
	v_exp_f32_e32 v141, v141
	v_add_f32_e32 v139, 1.0, v139
	v_add_f32_e32 v135, 1.0, v135
	v_add_f32_e32 v138, 1.0, v138
	v_rcp_f32_e32 v142, v139
	v_add_f32_e32 v139, 1.0, v141
	v_rcp_f32_e32 v134, v134
	v_rcp_f32_e32 v135, v135
	v_rcp_f32_e32 v143, v139
	v_rcp_f32_e32 v141, v138
	v_pk_mul_f32 v[138:139], v[38:39], v[136:137]
	v_pk_mul_f32 v[134:135], v[40:41], v[134:135]
	v_pk_mul_f32 v[136:137], v[36:37], v[142:143]
	v_pk_mul_f32 v[140:141], v[34:35], v[140:141]
.LBB0_193:
	v_lshl_add_u64 v[142:143], v[132:133], 0, s[18:19]
	v_cvt_pk_bf16_f32 v132, v138, v139
	v_cvt_pk_bf16_f32 v133, v134, v135
	v_cvt_pk_bf16_f32 v134, v140, v141
	v_cvt_pk_bf16_f32 v135, v136, v137
	global_store_dwordx4 v[142:143], v[132:135], off offset:64 sc1
	s_and_b64 vcc, exec, s[4:5]
	v_mov_b32_e32 v137, v29
	v_mov_b32_e32 v136, v28
	v_mov_b32_e32 v141, v27
	v_mov_b32_e32 v140, v26
	v_mov_b32_e32 v135, v33
	v_mov_b32_e32 v134, v32
	v_mov_b32_e32 v139, v31
	v_mov_b32_e32 v138, v30
	s_cbranch_vccnz .LBB0_195
	v_mul_f32_e32 v136, 0xbfb8aa3b, v26
	v_exp_f32_e32 v136, v136
	v_mul_f32_e32 v132, 0xbfb8aa3b, v30
	v_mul_f32_e32 v133, 0xbfb8aa3b, v31
	v_mul_f32_e32 v134, 0xbfb8aa3b, v32
	v_add_f32_e32 v136, 1.0, v136
	v_mul_f32_e32 v135, 0xbfb8aa3b, v33
	v_rcp_f32_e32 v140, v136
	v_mul_f32_e32 v136, 0xbfb8aa3b, v27
	v_mul_f32_e32 v137, 0xbfb8aa3b, v28
	v_mul_f32_e32 v138, 0xbfb8aa3b, v29
	v_exp_f32_e32 v132, v132
	v_exp_f32_e32 v133, v133
	v_exp_f32_e32 v134, v134
	v_exp_f32_e32 v135, v135
	v_exp_f32_e32 v136, v136
	v_exp_f32_e32 v137, v137
	v_exp_f32_e32 v138, v138
	v_add_f32_e32 v132, 1.0, v132
	v_add_f32_e32 v133, 1.0, v133
	v_add_f32_e32 v134, 1.0, v134
	v_add_f32_e32 v135, 1.0, v135
	v_add_f32_e32 v139, 1.0, v136
	v_add_f32_e32 v136, 1.0, v137
	v_add_f32_e32 v137, 1.0, v138
	v_rcp_f32_e32 v132, v132
	v_rcp_f32_e32 v133, v133
	v_rcp_f32_e32 v134, v134
	v_rcp_f32_e32 v135, v135
	v_rcp_f32_e32 v136, v136
	v_rcp_f32_e32 v137, v137
	v_rcp_f32_e32 v141, v139
	v_pk_mul_f32 v[134:135], v[32:33], v[134:135]
	v_pk_mul_f32 v[138:139], v[30:31], v[132:133]
	v_pk_mul_f32 v[136:137], v[28:29], v[136:137]
	v_pk_mul_f32 v[140:141], v[26:27], v[140:141]
; __device__ __forceinline__ unsigned cvt_pk_bf16(float lo, float hi) { unsigned r; asm volatile("v_cvt_pk_bf16_f32 %0, %1, %2" : "=v"(r) : "v"(lo), "v"(hi)); return r; }
; __device__ __forceinline__ float silu_f(float x) { return x * __builtin_amdgcn_rcpf(1.f + __expf(-x)); }
;     __device__ __forceinline__ void operator()(const f32x4 (&acc)[2][2][4][2], const pg8::Unit& u, int wr, int wc, int fr, int fq) const {
;     ...
; #pragma unroll
;             for (int ai = 0; ai < 2; ++ai)
; #pragma unroll
;                 for (int m = 0; m < 4; ++m) {
;                     bf16_t* rowp = base + (size_t)(row0 + ai * 128 + m * 16) * 512 + col0;
; #pragma unroll
;                     for (int bj = 0; bj < 2; ++bj) { f32x4 v0 = acc[ai][bj][m][0], v1 = acc[ai][bj][m][1];
;                         if (act) { v0 = (f32x4){silu_f(v0[0]), silu_f(v0[1]), silu_f(v0[2]), silu_f(v0[3])}; v1 = (f32x4){silu_f(v1[0]), silu_f(v1[1]), silu_f(v1[2]), silu_f(v1[3])}; }
;                         u32x4 w; w.x = cvt_pk_bf16(v0[0], v0[1]); w.y = cvt_pk_bf16(v0[2], v0[3]); w.z = cvt_pk_bf16(v1[0], v1[1]); w.w = cvt_pk_bf16(v1[2], v1[3]);
;                         *(u32x4*)(rowp + 32 * bj) = w; }
;                 }
.LBB0_195:
	v_lshlrev_b64 v[132:133], 10, v[172:173]
	v_lshl_add_u64 v[132:133], v[130:131], 0, v[132:133]
	v_cvt_pk_bf16_f32 v138, v138, v139
	v_cvt_pk_bf16_f32 v139, v134, v135
	v_add_co_u32_e32 v134, vcc, 0x28000, v132
	v_cvt_pk_bf16_f32 v140, v140, v141
	v_cvt_pk_bf16_f32 v141, v136, v137
	v_mov_b32_e32 v137, v21
	s_nop 0
	v_addc_co_u32_e32 v135, vcc, 0, v133, vcc
	global_store_dwordx4 v[134:135], v[138:141], off sc1
	s_and_b64 vcc, exec, s[4:5]
	v_mov_b32_e32 v136, v20
	v_mov_b32_e32 v141, v19
	v_mov_b32_e32 v140, v18
	v_mov_b32_e32 v135, v25
	v_mov_b32_e32 v134, v24
	v_mov_b32_e32 v139, v23
	v_mov_b32_e32 v138, v22
	s_cbranch_vccnz .LBB0_197
	v_mul_f32_e32 v134, 0xbfb8aa3b, v22
	v_exp_f32_e32 v134, v134
	v_mul_f32_e32 v135, 0xbfb8aa3b, v23
	v_mul_f32_e32 v136, 0xbfb8aa3b, v24
	v_exp_f32_e32 v135, v135
	v_exp_f32_e32 v138, v136
	v_add_f32_e32 v134, 1.0, v134
	v_rcp_f32_e32 v136, v134
	v_add_f32_e32 v134, 1.0, v135
	v_rcp_f32_e32 v137, v134
	v_add_f32_e32 v134, 1.0, v138
	v_mul_f32_e32 v138, 0xbfb8aa3b, v18
	v_exp_f32_e32 v138, v138
	v_mul_f32_e32 v139, 0xbfb8aa3b, v20
	v_mul_f32_e32 v135, 0xbfb8aa3b, v25
	v_exp_f32_e32 v139, v139
	v_add_f32_e32 v138, 1.0, v138
	v_rcp_f32_e32 v140, v138
	v_mul_f32_e32 v138, 0xbfb8aa3b, v19
	v_mul_f32_e32 v141, 0xbfb8aa3b, v21
	v_exp_f32_e32 v135, v135
	v_exp_f32_e32 v138, v138
	v_exp_f32_e32 v141, v141
	v_add_f32_e32 v139, 1.0, v139
	v_add_f32_e32 v135, 1.0, v135
	v_add_f32_e32 v138, 1.0, v138
	v_rcp_f32_e32 v142, v139
	v_add_f32_e32 v139, 1.0, v141
	v_rcp_f32_e32 v134, v134
	v_rcp_f32_e32 v135, v135
	v_rcp_f32_e32 v143, v139
	v_rcp_f32_e32 v141, v138
	v_pk_mul_f32 v[138:139], v[22:23], v[136:137]
	v_pk_mul_f32 v[134:135], v[24:25], v[134:135]
	v_pk_mul_f32 v[136:137], v[20:21], v[142:143]
	v_pk_mul_f32 v[140:141], v[18:19], v[140:141]
.LBB0_197:
	v_lshl_add_u64 v[142:143], v[132:133], 0, s[20:21]
	v_cvt_pk_bf16_f32 v132, v138, v139
	v_cvt_pk_bf16_f32 v133, v134, v135
	v_cvt_pk_bf16_f32 v134, v140, v141
	v_cvt_pk_bf16_f32 v135, v136, v137
	global_store_dwordx4 v[142:143], v[132:135], off offset:64 sc1
	s_and_b64 vcc, exec, s[4:5]
	v_mov_b32_e32 v139, v11
	v_mov_b32_e32 v135, v13
	v_mov_b32_e32 v134, v12
	v_mov_b32_e32 v138, v10
	v_mov_b32_e32 v133, v17
	v_mov_b32_e32 v132, v16
	v_mov_b32_e32 v137, v15
	v_mov_b32_e32 v136, v14
	s_cbranch_vccnz .LBB0_199
	v_mul_f32_e32 v132, 0xbfb8aa3b, v14
	v_exp_f32_e32 v132, v132
	v_mul_f32_e32 v133, 0xbfb8aa3b, v15
	v_mul_f32_e32 v134, 0xbfb8aa3b, v16
	v_exp_f32_e32 v133, v133
	v_exp_f32_e32 v136, v134
	v_add_f32_e32 v132, 1.0, v132
	v_rcp_f32_e32 v134, v132
	v_add_f32_e32 v132, 1.0, v133
	v_rcp_f32_e32 v135, v132
	v_add_f32_e32 v132, 1.0, v136
	v_mul_f32_e32 v136, 0xbfb8aa3b, v10
	v_exp_f32_e32 v136, v136
	v_mul_f32_e32 v137, 0xbfb8aa3b, v12
	v_mul_f32_e32 v133, 0xbfb8aa3b, v17
	v_exp_f32_e32 v137, v137
	v_add_f32_e32 v136, 1.0, v136
	v_rcp_f32_e32 v138, v136
	v_mul_f32_e32 v136, 0xbfb8aa3b, v11
	v_mul_f32_e32 v139, 0xbfb8aa3b, v13
	v_exp_f32_e32 v133, v133
	v_exp_f32_e32 v136, v136
	v_exp_f32_e32 v139, v139
	v_add_f32_e32 v137, 1.0, v137
	v_add_f32_e32 v133, 1.0, v133
	v_add_f32_e32 v136, 1.0, v136
	v_rcp_f32_e32 v140, v137
	v_add_f32_e32 v137, 1.0, v139
	v_rcp_f32_e32 v132, v132
	v_rcp_f32_e32 v133, v133
	v_rcp_f32_e32 v141, v137
	v_rcp_f32_e32 v139, v136
	v_pk_mul_f32 v[136:137], v[14:15], v[134:135]
	v_pk_mul_f32 v[132:133], v[16:17], v[132:133]
	v_pk_mul_f32 v[134:135], v[12:13], v[140:141]
	v_pk_mul_f32 v[138:139], v[10:11], v[138:139]
.LBB0_199:
	v_lshlrev_b64 v[140:141], 10, v[172:173]
	v_lshl_add_u64 v[130:131], v[130:131], 0, v[140:141]
	v_cvt_pk_bf16_f32 v136, v136, v137
	v_cvt_pk_bf16_f32 v137, v132, v133
	v_add_co_u32_e32 v132, vcc, 0x2c000, v130
	v_cvt_pk_bf16_f32 v138, v138, v139
	v_cvt_pk_bf16_f32 v139, v134, v135
	v_mov_b32_e32 v135, v9
	s_nop 0
	v_addc_co_u32_e32 v133, vcc, 0, v131, vcc
	global_store_dwordx4 v[132:133], v[136:139], off sc1
	s_and_b64 vcc, exec, s[4:5]
	v_mov_b32_e32 v133, v5
	v_mov_b32_e32 v132, v4
	v_mov_b32_e32 v137, v3
	v_mov_b32_e32 v136, v2
	v_mov_b32_e32 v134, v8
	v_mov_b32_e32 v139, v7
	v_mov_b32_e32 v138, v6
	s_cbranch_vccnz .LBB0_201
	v_mul_f32_e32 v138, 0xbfb8aa3b, v4
	v_mul_f32_e32 v132, 0xbfb8aa3b, v6
	v_mul_f32_e32 v133, 0xbfb8aa3b, v7
	v_mul_f32_e32 v134, 0xbfb8aa3b, v8
	v_mul_f32_e32 v135, 0xbfb8aa3b, v9
	v_mul_f32_e32 v136, 0xbfb8aa3b, v2
	v_mul_f32_e32 v137, 0xbfb8aa3b, v3
	v_exp_f32_e32 v138, v138
	v_mul_f32_e32 v139, 0xbfb8aa3b, v5
	v_exp_f32_e32 v132, v132
	v_exp_f32_e32 v133, v133
	v_exp_f32_e32 v134, v134
	v_exp_f32_e32 v135, v135
	v_exp_f32_e32 v136, v136
	v_exp_f32_e32 v137, v137
	v_exp_f32_e32 v139, v139
	v_add_f32_e32 v138, 1.0, v138
	v_add_f32_e32 v132, 1.0, v132
	v_add_f32_e32 v133, 1.0, v133
	v_add_f32_e32 v134, 1.0, v134
	v_add_f32_e32 v135, 1.0, v135
	v_add_f32_e32 v136, 1.0, v136
	v_add_f32_e32 v137, 1.0, v137
	v_rcp_f32_e32 v140, v138
	v_add_f32_e32 v138, 1.0, v139
	v_rcp_f32_e32 v132, v132
	v_rcp_f32_e32 v133, v133
	v_rcp_f32_e32 v134, v134
	v_rcp_f32_e32 v135, v135
	v_rcp_f32_e32 v136, v136
	v_rcp_f32_e32 v141, v138
	v_rcp_f32_e32 v137, v137
	v_pk_mul_f32 v[134:135], v[8:9], v[134:135]
	v_pk_mul_f32 v[138:139], v[6:7], v[132:133]
	v_pk_mul_f32 v[132:133], v[4:5], v[140:141]
	v_pk_mul_f32 v[136:137], v[2:3], v[136:137]
.LBB0_201:
	v_lshl_add_u64 v[130:131], v[130:131], 0, s[24:25]
	v_cvt_pk_bf16_f32 v138, v138, v139
	v_cvt_pk_bf16_f32 v139, v134, v135
	v_cvt_pk_bf16_f32 v140, v136, v137
	v_cvt_pk_bf16_f32 v141, v132, v133
	global_store_dwordx4 v[130:131], v[138:141], off offset:64 sc1
	s_mov_b64 s[4:5], 0
; __device__ __forceinline__ unsigned cvt_pk_bf16(float lo, float hi) { unsigned r; asm volatile("v_cvt_pk_bf16_f32 %0, %1, %2" : "=v"(r) : "v"(lo), "v"(hi)); return r; }
;     __device__ __forceinline__ void operator()(const f32x4 (&acc)[2][2][4][2], const pg8::Unit& u, int wr, int wc, int fr, int fq) const {
;     ...
;         } else if (sec == 4 || sec == 5) {
;             const float osc = sec == 5 ? 0.08838834764831845f : 1.f;
;             const int col0 = 256 * half + 128 * (wc >> 1) + 32 * (wc & 1) + 8 * fq, i0 = 32 * (wc & 1) + 8 * fq;
;             const int tb = row0 < NP ? (row0 & 4095) : row0 - NP;
;             f32x4 c[2], sn[2], c16[2], s16[2];
; #pragma unroll
;             for (int e = 0; e < 2; ++e) { c[e] = *(const f32x4*)(ropec + tb * 64 + i0 + 4 * e); sn[e] = *(const f32x4*)(ropes + tb * 64 + i0 + 4 * e);
;                 c16[e] = *(const f32x4*)(ropec + 16 * 64 + i0 + 4 * e); s16[e] = *(const f32x4*)(ropes + 16 * 64 + i0 + 4 * e); }
;             asm volatile("" ::: "memory");
; #pragma unroll
;             for (int k = 0; k < 12; ++k) {
;                 if (k < 4 || k >= 8) {
;                     const int ai = k >> 3, m = k & 3;
;                     const int row = row0 + ai * 128 + m * 16;
;                     const f32x4 c0 = c[0] * osc, c1 = c[1] * osc, s0 = sn[0] * osc, s1 = sn[1] * osc;
;                     const f32x4 a0 = acc[ai][0][m][0], a1 = acc[ai][0][m][1], b0 = acc[ai][1][m][0], b1 = acc[ai][1][m][1];
;                     const f32x4 o10 = a0 * c0 - b0 * s0, o11 = a1 * c1 - b1 * s1, o20 = a0 * s0 + b0 * c0, o21 = a1 * s1 + b1 * c1;
;                     bf16_t* rowp = base + (size_t)row * 512 + col0;
;                     u32x4 w; w.x = cvt_pk_bf16(o10[0], o10[1]); w.y = cvt_pk_bf16(o10[2], o10[3]); w.z = cvt_pk_bf16(o11[0], o11[1]); w.w = cvt_pk_bf16(o11[2], o11[3]);
;                     *(u32x4*)(rowp) = w;
;                     w.x = cvt_pk_bf16(o20[0], o20[1]); w.y = cvt_pk_bf16(o20[2], o20[3]); w.z = cvt_pk_bf16(o21[0], o21[1]); w.w = cvt_pk_bf16(o21[2], o21[3]);
;                     *(u32x4*)(rowp + 64) = w;
.LBB0_202:
	s_and_b64 vcc, exec, s[4:5]
	s_cbranch_vccz .LBB0_204
	v_and_b32_e32 v130, 0xfcf, v172
	v_add_u32_e32 v131, 0xffff0000, v172
	v_cmp_gt_i32_e32 vcc, s77, v172
	s_cmp_eq_u32 s41, 5
	v_lshl_or_b32 v154, s27, 9, v186
	v_cndmask_b32_e32 v130, v131, v130, vcc
	v_lshlrev_b32_e32 v130, 6, v130
	v_ashrrev_i32_e32 v131, 31, v130
	v_lshlrev_b64 v[130:131], 2, v[130:131]
	v_lshl_add_u64 v[132:133], v[156:157], 0, v[130:131]
	global_load_dwordx4 v[192:195], v[132:133], off
	global_load_dwordx4 v[196:199], v[132:133], off offset:16
	v_lshl_add_u64 v[130:131], v[158:159], 0, v[130:131]
	global_load_dwordx4 v[200:203], v[130:131], off
	global_load_dwordx4 v[204:207], v[130:131], off offset:16
	global_load_dwordx4 v[142:145], v[162:163], off
	global_load_dwordx4 v[134:137], v[162:163], off offset:16
	global_load_dwordx4 v[138:141], v[160:161], off
	s_nop 0
	global_load_dwordx4 v[130:133], v[160:161], off offset:16
	s_cselect_b64 vcc, -1, 0
	v_cndmask_b32_e32 v176, 1.0, v189, vcc
	v_ashrrev_i32_e32 v173, 31, v172
	v_lshl_add_u64 v[178:179], s[48:49], 0, v[154:155]
	v_lshlrev_b64 v[174:175], 10, v[172:173]
	v_lshl_add_u64 v[174:175], v[178:179], 0, v[174:175]
	v_or_b32_e32 v208, 16, v172
	v_ashrrev_i32_e32 v209, 31, v208
	s_waitcnt vmcnt(0)
	v_pk_mul_f32 v[220:221], v[176:177], v[200:201] op_sel_hi:[0,1]
	v_pk_mul_f32 v[218:219], v[176:177], v[202:203] op_sel_hi:[0,1]
	v_pk_mul_f32 v[212:213], v[176:177], v[192:193] op_sel_hi:[0,1]
	v_pk_mul_f32 v[228:229], v[200:201], v[142:143]
	v_pk_mul_f32 v[244:245], v[118:119], v[220:221]
	v_pk_mul_f32 v[210:211], v[176:177], v[194:195] op_sel_hi:[0,1]
	v_pk_mul_f32 v[222:223], v[176:177], v[206:207] op_sel_hi:[0,1]
	v_pk_mul_f32 v[224:225], v[176:177], v[204:205] op_sel_hi:[0,1]
	v_pk_mul_f32 v[226:227], v[202:203], v[144:145]
	v_pk_mul_f32 v[230:231], v[194:195], v[144:145]
	v_pk_mul_f32 v[232:233], v[192:193], v[142:143]
	v_pk_mul_f32 v[242:243], v[120:121], v[218:219]
	v_pk_fma_f32 v[228:229], v[192:193], v[138:139], v[228:229] neg_lo:[0,0,1] neg_hi:[0,0,1]
	v_pk_fma_f32 v[192:193], v[126:127], v[212:213], v[244:245] neg_lo:[0,0,1] neg_hi:[0,0,1]
	v_pk_mul_f32 v[214:215], v[176:177], v[198:199] op_sel_hi:[0,1]
	v_pk_mul_f32 v[216:217], v[176:177], v[196:197] op_sel_hi:[0,1]
	v_pk_mul_f32 v[234:235], v[206:207], v[136:137]
	v_pk_mul_f32 v[238:239], v[198:199], v[136:137]
	v_pk_mul_f32 v[240:241], v[196:197], v[134:135]
	v_pk_mul_f32 v[246:247], v[116:117], v[222:223]
	v_pk_mul_f32 v[248:249], v[114:115], v[224:225]
	v_pk_mul_f32 v[218:219], v[128:129], v[218:219]
	v_pk_mul_f32 v[220:221], v[126:127], v[220:221]
	v_pk_fma_f32 v[226:227], v[194:195], v[140:141], v[226:227] neg_lo:[0,0,1] neg_hi:[0,0,1]
	v_pk_fma_f32 v[202:203], v[202:203], v[140:141], v[230:231]
	v_pk_fma_f32 v[194:195], v[128:129], v[210:211], v[242:243] neg_lo:[0,0,1] neg_hi:[0,0,1]
	v_cvt_pk_bf16_f32 v192, v192, v193
	v_pk_mul_f32 v[236:237], v[204:205], v[134:135]
	v_cvt_pk_bf16_f32 v193, v194, v195
	v_pk_mul_f32 v[222:223], v[124:125], v[222:223]
	v_pk_mul_f32 v[224:225], v[122:123], v[224:225]
	v_pk_fma_f32 v[200:201], v[200:201], v[138:139], v[232:233]
	v_pk_fma_f32 v[198:199], v[198:199], v[132:133], v[234:235] neg_lo:[0,0,1] neg_hi:[0,0,1]
	v_pk_fma_f32 v[206:207], v[206:207], v[132:133], v[238:239]
	v_pk_fma_f32 v[204:205], v[204:205], v[130:131], v[240:241]
	v_pk_fma_f32 v[230:231], v[124:125], v[214:215], v[246:247] neg_lo:[0,0,1] neg_hi:[0,0,1]
	v_pk_fma_f32 v[232:233], v[122:123], v[216:217], v[248:249] neg_lo:[0,0,1] neg_hi:[0,0,1]
	v_pk_fma_f32 v[210:211], v[120:121], v[210:211], v[218:219]
	v_pk_fma_f32 v[212:213], v[118:119], v[212:213], v[220:221]
	v_pk_mul_f32 v[218:219], v[176:177], v[226:227] op_sel_hi:[0,1]
	v_pk_mul_f32 v[234:235], v[176:177], v[202:203] op_sel_hi:[0,1]
	v_cvt_pk_bf16_f32 v194, v232, v233
	v_cvt_pk_bf16_f32 v195, v230, v231
	global_store_dwordx4 v[174:175], v[192:195], off sc1
	v_pk_fma_f32 v[196:197], v[196:197], v[130:131], v[236:237] neg_lo:[0,0,1] neg_hi:[0,0,1]
	v_pk_fma_f32 v[214:215], v[116:117], v[214:215], v[222:223]
	v_cvt_pk_bf16_f32 v192, v212, v213
	v_cvt_pk_bf16_f32 v193, v210, v211
	v_pk_fma_f32 v[216:217], v[114:115], v[216:217], v[224:225]
	v_pk_mul_f32 v[222:223], v[176:177], v[198:199] op_sel_hi:[0,1]
	v_pk_mul_f32 v[238:239], v[176:177], v[206:207] op_sel_hi:[0,1]
	v_pk_mul_f32 v[240:241], v[176:177], v[204:205] op_sel_hi:[0,1]
	v_pk_mul_f32 v[230:231], v[104:105], v[234:235]
	v_cvt_pk_bf16_f32 v194, v216, v217
	v_cvt_pk_bf16_f32 v195, v214, v215
	global_store_dwordx4 v[174:175], v[192:195], off offset:128 sc1
	v_pk_mul_f32 v[224:225], v[176:177], v[196:197] op_sel_hi:[0,1]
	v_pk_mul_f32 v[236:237], v[176:177], v[200:201] op_sel_hi:[0,1]
	v_pk_mul_f32 v[192:193], v[104:105], v[218:219]
	v_pk_mul_f32 v[242:243], v[100:101], v[238:239]
	v_pk_mul_f32 v[244:245], v[98:99], v[240:241]
	v_pk_fma_f32 v[210:211], v[112:113], v[218:219], v[230:231] neg_lo:[0,0,1] neg_hi:[0,0,1]
	v_pk_fma_f32 v[218:219], v[112:113], v[234:235], v[192:193]
	v_pk_mul_f32 v[192:193], v[100:101], v[222:223]
	v_pk_mul_f32 v[220:221], v[176:177], v[228:229] op_sel_hi:[0,1]
	v_pk_mul_f32 v[232:233], v[102:103], v[236:237]
	v_pk_fma_f32 v[214:215], v[108:109], v[222:223], v[242:243] neg_lo:[0,0,1] neg_hi:[0,0,1]
	v_pk_fma_f32 v[194:195], v[106:107], v[224:225], v[244:245] neg_lo:[0,0,1] neg_hi:[0,0,1]
	v_pk_fma_f32 v[222:223], v[108:109], v[238:239], v[192:193]
	v_lshlrev_b64 v[192:193], 10, v[208:209]
	v_pk_fma_f32 v[212:213], v[110:111], v[220:221], v[232:233] neg_lo:[0,0,1] neg_hi:[0,0,1]
	v_pk_mul_f32 v[216:217], v[102:103], v[220:221]
	v_pk_mul_f32 v[220:221], v[98:99], v[224:225]
; __device__ __forceinline__ unsigned cvt_pk_bf16(float lo, float hi) { unsigned r; asm volatile("v_cvt_pk_bf16_f32 %0, %1, %2" : "=v"(r) : "v"(lo), "v"(hi)); return r; }
;     __device__ __forceinline__ void operator()(const f32x4 (&acc)[2][2][4][2], const pg8::Unit& u, int wr, int wc, int fr, int fq) const {
;     ...
; #pragma unroll
;             for (int k = 0; k < 12; ++k) {
;                 if (k < 4 || k >= 8) {
;                     const int ai = k >> 3, m = k & 3;
;                     const int row = row0 + ai * 128 + m * 16;
;                     const f32x4 c0 = c[0] * osc, c1 = c[1] * osc, s0 = sn[0] * osc, s1 = sn[1] * osc;
;                     const f32x4 a0 = acc[ai][0][m][0], a1 = acc[ai][0][m][1], b0 = acc[ai][1][m][0], b1 = acc[ai][1][m][1];
;                     const f32x4 o10 = a0 * c0 - b0 * s0, o11 = a1 * c1 - b1 * s1, o20 = a0 * s0 + b0 * c0, o21 = a1 * s1 + b1 * c1;
;                     bf16_t* rowp = base + (size_t)row * 512 + col0;
;                     u32x4 w; w.x = cvt_pk_bf16(o10[0], o10[1]); w.y = cvt_pk_bf16(o10[2], o10[3]); w.z = cvt_pk_bf16(o11[0], o11[1]); w.w = cvt_pk_bf16(o11[2], o11[3]);
;                     *(u32x4*)(rowp) = w;
;                     w.x = cvt_pk_bf16(o20[0], o20[1]); w.y = cvt_pk_bf16(o20[2], o20[3]); w.z = cvt_pk_bf16(o21[0], o21[1]); w.w = cvt_pk_bf16(o21[2], o21[3]);
;                     *(u32x4*)(rowp + 64) = w;
;                 }
;                 if (k < 11) {
; #pragma unroll
;                     for (int e = 0; e < 2; ++e) { const f32x4 cn = c[e] * c16[e] - sn[e] * s16[e]; sn[e] = sn[e] * c16[e] + c[e] * s16[e]; c[e] = cn; } }
	v_lshl_add_u64 v[208:209], v[178:179], 0, v[192:193]
	v_cvt_pk_bf16_f32 v192, v212, v213
	v_cvt_pk_bf16_f32 v193, v210, v211
	v_cvt_pk_bf16_f32 v194, v194, v195
	v_cvt_pk_bf16_f32 v195, v214, v215
	v_pk_fma_f32 v[216:217], v[110:111], v[236:237], v[216:217]
	v_pk_fma_f32 v[220:221], v[106:107], v[240:241], v[220:221]
	global_store_dwordx4 v[208:209], v[192:195], off sc1
	s_nop 1
	v_cvt_pk_bf16_f32 v192, v216, v217
	v_cvt_pk_bf16_f32 v193, v218, v219
	v_cvt_pk_bf16_f32 v194, v220, v221
	v_cvt_pk_bf16_f32 v195, v222, v223
	global_store_dwordx4 v[208:209], v[192:195], off offset:128 sc1
	s_nop 1
	v_pk_mul_f32 v[192:193], v[144:145], v[202:203]
	v_pk_mul_f32 v[194:195], v[142:143], v[200:201]
	v_pk_fma_f32 v[208:209], v[140:141], v[226:227], v[192:193] neg_lo:[0,0,1] neg_hi:[0,0,1]
	v_pk_fma_f32 v[210:211], v[138:139], v[228:229], v[194:195] neg_lo:[0,0,1] neg_hi:[0,0,1]
	v_pk_mul_f32 v[192:193], v[144:145], v[226:227]
	v_pk_mul_f32 v[194:195], v[142:143], v[228:229]
	v_pk_fma_f32 v[202:203], v[140:141], v[202:203], v[192:193]
	v_pk_fma_f32 v[200:201], v[138:139], v[200:201], v[194:195]
	v_pk_mul_f32 v[192:193], v[136:137], v[206:207]
	v_pk_mul_f32 v[194:195], v[134:135], v[204:205]
	v_pk_fma_f32 v[212:213], v[132:133], v[198:199], v[192:193] neg_lo:[0,0,1] neg_hi:[0,0,1]
	v_pk_fma_f32 v[214:215], v[130:131], v[196:197], v[194:195] neg_lo:[0,0,1] neg_hi:[0,0,1]
	v_pk_mul_f32 v[192:193], v[136:137], v[198:199]
	v_pk_mul_f32 v[194:195], v[134:135], v[196:197]
	v_pk_mul_f32 v[218:219], v[176:177], v[202:203] op_sel_hi:[0,1]
	v_pk_fma_f32 v[196:197], v[132:133], v[206:207], v[192:193]
	v_pk_fma_f32 v[198:199], v[130:131], v[204:205], v[194:195]
	v_or_b32_e32 v192, 32, v172
	v_pk_mul_f32 v[194:195], v[176:177], v[208:209] op_sel_hi:[0,1]
	v_pk_mul_f32 v[220:221], v[176:177], v[200:201] op_sel_hi:[0,1]
	v_pk_mul_f32 v[226:227], v[88:89], v[218:219]
	v_pk_mul_f32 v[204:205], v[176:177], v[210:211] op_sel_hi:[0,1]
	v_pk_mul_f32 v[206:207], v[176:177], v[212:213] op_sel_hi:[0,1]
	v_pk_mul_f32 v[222:223], v[176:177], v[196:197] op_sel_hi:[0,1]
	v_pk_mul_f32 v[224:225], v[176:177], v[198:199] op_sel_hi:[0,1]
	v_pk_mul_f32 v[228:229], v[86:87], v[220:221]
	v_pk_fma_f32 v[226:227], v[96:97], v[194:195], v[226:227] neg_lo:[0,0,1] neg_hi:[0,0,1]
	v_pk_mul_f32 v[194:195], v[88:89], v[194:195]
	v_ashrrev_i32_e32 v193, 31, v192
	v_pk_mul_f32 v[216:217], v[176:177], v[214:215] op_sel_hi:[0,1]
	v_pk_fma_f32 v[228:229], v[94:95], v[204:205], v[228:229] neg_lo:[0,0,1] neg_hi:[0,0,1]
	v_pk_mul_f32 v[230:231], v[84:85], v[222:223]
	v_pk_mul_f32 v[232:233], v[82:83], v[224:225]
	v_pk_mul_f32 v[204:205], v[86:87], v[204:205]
	v_pk_fma_f32 v[218:219], v[96:97], v[218:219], v[194:195]
	v_pk_mul_f32 v[194:195], v[84:85], v[206:207]
	v_lshlrev_b64 v[192:193], 10, v[192:193]
	v_pk_fma_f32 v[230:231], v[92:93], v[206:207], v[230:231] neg_lo:[0,0,1] neg_hi:[0,0,1]
	v_pk_fma_f32 v[232:233], v[90:91], v[216:217], v[232:233] neg_lo:[0,0,1] neg_hi:[0,0,1]
	v_pk_fma_f32 v[204:205], v[94:95], v[220:221], v[204:205]
	v_pk_mul_f32 v[206:207], v[82:83], v[216:217]
	v_pk_fma_f32 v[216:217], v[92:93], v[222:223], v[194:195]
	v_lshl_add_u64 v[220:221], v[178:179], 0, v[192:193]
	v_cvt_pk_bf16_f32 v192, v228, v229
	v_cvt_pk_bf16_f32 v193, v226, v227
	v_cvt_pk_bf16_f32 v194, v232, v233
	v_cvt_pk_bf16_f32 v195, v230, v231
	v_pk_fma_f32 v[206:207], v[90:91], v[224:225], v[206:207]
	global_store_dwordx4 v[220:221], v[192:195], off sc1
	s_nop 1
	v_cvt_pk_bf16_f32 v192, v204, v205
	v_cvt_pk_bf16_f32 v193, v218, v219
	v_cvt_pk_bf16_f32 v194, v206, v207
	v_cvt_pk_bf16_f32 v195, v216, v217
	global_store_dwordx4 v[220:221], v[192:195], off offset:128 sc1
	s_nop 1
	v_pk_mul_f32 v[192:193], v[144:145], v[202:203]
	v_pk_mul_f32 v[194:195], v[142:143], v[200:201]
	v_pk_fma_f32 v[204:205], v[140:141], v[208:209], v[192:193] neg_lo:[0,0,1] neg_hi:[0,0,1]
	v_pk_fma_f32 v[206:207], v[138:139], v[210:211], v[194:195] neg_lo:[0,0,1] neg_hi:[0,0,1]
	v_pk_mul_f32 v[192:193], v[144:145], v[208:209]
	v_pk_mul_f32 v[194:195], v[142:143], v[210:211]
	v_pk_fma_f32 v[202:203], v[140:141], v[202:203], v[192:193]
	v_pk_fma_f32 v[200:201], v[138:139], v[200:201], v[194:195]
	v_pk_mul_f32 v[192:193], v[136:137], v[196:197]
	v_pk_mul_f32 v[194:195], v[134:135], v[198:199]
	v_pk_fma_f32 v[208:209], v[132:133], v[212:213], v[192:193] neg_lo:[0,0,1] neg_hi:[0,0,1]
	v_pk_fma_f32 v[210:211], v[130:131], v[214:215], v[194:195] neg_lo:[0,0,1] neg_hi:[0,0,1]
	v_pk_mul_f32 v[192:193], v[136:137], v[212:213]
	v_pk_mul_f32 v[194:195], v[134:135], v[214:215]
	v_pk_mul_f32 v[218:219], v[176:177], v[202:203] op_sel_hi:[0,1]
	v_pk_fma_f32 v[196:197], v[132:133], v[196:197], v[192:193]
	v_pk_fma_f32 v[198:199], v[130:131], v[198:199], v[194:195]
	v_or_b32_e32 v192, 48, v172
	v_pk_mul_f32 v[194:195], v[176:177], v[204:205] op_sel_hi:[0,1]
	v_pk_mul_f32 v[226:227], v[72:73], v[218:219]
	v_pk_mul_f32 v[214:215], v[176:177], v[208:209] op_sel_hi:[0,1]
	v_pk_mul_f32 v[220:221], v[176:177], v[200:201] op_sel_hi:[0,1]
	v_pk_mul_f32 v[222:223], v[176:177], v[196:197] op_sel_hi:[0,1]
	v_pk_mul_f32 v[224:225], v[176:177], v[198:199] op_sel_hi:[0,1]
	v_pk_fma_f32 v[226:227], v[80:81], v[194:195], v[226:227] neg_lo:[0,0,1] neg_hi:[0,0,1]
	v_pk_mul_f32 v[194:195], v[72:73], v[194:195]
	v_ashrrev_i32_e32 v193, 31, v192
	v_pk_mul_f32 v[212:213], v[176:177], v[206:207] op_sel_hi:[0,1]
	v_pk_mul_f32 v[216:217], v[176:177], v[210:211] op_sel_hi:[0,1]
	v_pk_mul_f32 v[228:229], v[70:71], v[220:221]
	v_pk_mul_f32 v[230:231], v[68:69], v[222:223]
	v_pk_mul_f32 v[232:233], v[66:67], v[224:225]
	v_pk_fma_f32 v[218:219], v[80:81], v[218:219], v[194:195]
; __device__ __forceinline__ unsigned cvt_pk_bf16(float lo, float hi) { unsigned r; asm volatile("v_cvt_pk_bf16_f32 %0, %1, %2" : "=v"(r) : "v"(lo), "v"(hi)); return r; }
;     __device__ __forceinline__ void operator()(const f32x4 (&acc)[2][2][4][2], const pg8::Unit& u, int wr, int wc, int fr, int fq) const {
;     ...
;             for (int k = 0; k < 12; ++k) {
;                 if (k < 4 || k >= 8) {
;                     const int ai = k >> 3, m = k & 3;
;                     const int row = row0 + ai * 128 + m * 16;
;                     const f32x4 c0 = c[0] * osc, c1 = c[1] * osc, s0 = sn[0] * osc, s1 = sn[1] * osc;
;                     const f32x4 a0 = acc[ai][0][m][0], a1 = acc[ai][0][m][1], b0 = acc[ai][1][m][0], b1 = acc[ai][1][m][1];
;                     const f32x4 o10 = a0 * c0 - b0 * s0, o11 = a1 * c1 - b1 * s1, o20 = a0 * s0 + b0 * c0, o21 = a1 * s1 + b1 * c1;
;                     bf16_t* rowp = base + (size_t)row * 512 + col0;
;                     u32x4 w; w.x = cvt_pk_bf16(o10[0], o10[1]); w.y = cvt_pk_bf16(o10[2], o10[3]); w.z = cvt_pk_bf16(o11[0], o11[1]); w.w = cvt_pk_bf16(o11[2], o11[3]);
;                     *(u32x4*)(rowp) = w;
;                     w.x = cvt_pk_bf16(o20[0], o20[1]); w.y = cvt_pk_bf16(o20[2], o20[3]); w.z = cvt_pk_bf16(o21[0], o21[1]); w.w = cvt_pk_bf16(o21[2], o21[3]);
;                     *(u32x4*)(rowp + 64) = w;
;                 }
;                 if (k < 11) {
; #pragma unroll
;                     for (int e = 0; e < 2; ++e) { const f32x4 cn = c[e] * c16[e] - sn[e] * s16[e]; sn[e] = sn[e] * c16[e] + c[e] * s16[e]; c[e] = cn; } }
	v_pk_mul_f32 v[194:195], v[68:69], v[214:215]
	v_lshlrev_b64 v[192:193], 10, v[192:193]
	v_pk_fma_f32 v[228:229], v[78:79], v[212:213], v[228:229] neg_lo:[0,0,1] neg_hi:[0,0,1]
	v_pk_fma_f32 v[230:231], v[76:77], v[214:215], v[230:231] neg_lo:[0,0,1] neg_hi:[0,0,1]
	v_pk_fma_f32 v[232:233], v[74:75], v[216:217], v[232:233] neg_lo:[0,0,1] neg_hi:[0,0,1]
	v_pk_mul_f32 v[212:213], v[70:71], v[212:213]
	v_pk_mul_f32 v[214:215], v[66:67], v[216:217]
	v_pk_fma_f32 v[216:217], v[76:77], v[222:223], v[194:195]
	v_lshl_add_u64 v[178:179], v[178:179], 0, v[192:193]
	v_cvt_pk_bf16_f32 v192, v228, v229
	v_cvt_pk_bf16_f32 v193, v226, v227
	v_cvt_pk_bf16_f32 v194, v232, v233
	v_cvt_pk_bf16_f32 v195, v230, v231
	v_pk_fma_f32 v[212:213], v[78:79], v[220:221], v[212:213]
	v_pk_fma_f32 v[214:215], v[74:75], v[224:225], v[214:215]
	global_store_dwordx4 v[178:179], v[192:195], off sc1
	s_nop 1
	v_cvt_pk_bf16_f32 v192, v212, v213
	v_cvt_pk_bf16_f32 v193, v218, v219
	v_cvt_pk_bf16_f32 v194, v214, v215
	v_cvt_pk_bf16_f32 v195, v216, v217
	global_store_dwordx4 v[178:179], v[192:195], off offset:128 sc1
	v_pk_mul_f32 v[178:179], v[144:145], v[202:203]
	s_nop 0
	v_pk_mul_f32 v[194:195], v[144:145], v[204:205]
	v_pk_mul_f32 v[192:193], v[142:143], v[200:201]
	v_pk_fma_f32 v[178:179], v[140:141], v[204:205], v[178:179] neg_lo:[0,0,1] neg_hi:[0,0,1]
	v_pk_mul_f32 v[204:205], v[142:143], v[206:207]
	v_pk_fma_f32 v[194:195], v[140:141], v[202:203], v[194:195]
	v_pk_mul_f32 v[202:203], v[136:137], v[196:197]
	v_pk_fma_f32 v[192:193], v[138:139], v[206:207], v[192:193] neg_lo:[0,0,1] neg_hi:[0,0,1]
	v_pk_fma_f32 v[200:201], v[138:139], v[200:201], v[204:205]
	v_pk_fma_f32 v[202:203], v[132:133], v[208:209], v[202:203] neg_lo:[0,0,1] neg_hi:[0,0,1]
	v_pk_mul_f32 v[206:207], v[136:137], v[208:209]
	v_pk_mul_f32 v[208:209], v[134:135], v[210:211]
	v_pk_mul_f32 v[204:205], v[134:135], v[198:199]
	v_pk_fma_f32 v[196:197], v[132:133], v[196:197], v[206:207]
	v_pk_fma_f32 v[198:199], v[130:131], v[198:199], v[208:209]
	v_pk_mul_f32 v[206:207], v[144:145], v[194:195]
	v_pk_mul_f32 v[208:209], v[142:143], v[200:201]
	v_pk_fma_f32 v[206:207], v[140:141], v[178:179], v[206:207] neg_lo:[0,0,1] neg_hi:[0,0,1]
	v_pk_fma_f32 v[208:209], v[138:139], v[192:193], v[208:209] neg_lo:[0,0,1] neg_hi:[0,0,1]
	v_pk_mul_f32 v[178:179], v[144:145], v[178:179]
	v_pk_mul_f32 v[192:193], v[142:143], v[192:193]
	v_pk_fma_f32 v[204:205], v[130:131], v[210:211], v[204:205] neg_lo:[0,0,1] neg_hi:[0,0,1]
	v_pk_fma_f32 v[178:179], v[140:141], v[194:195], v[178:179]
	v_pk_fma_f32 v[192:193], v[138:139], v[200:201], v[192:193]
	v_pk_mul_f32 v[194:195], v[136:137], v[196:197]
	v_pk_mul_f32 v[200:201], v[134:135], v[198:199]
	v_pk_fma_f32 v[194:195], v[132:133], v[202:203], v[194:195] neg_lo:[0,0,1] neg_hi:[0,0,1]
	v_pk_fma_f32 v[200:201], v[130:131], v[204:205], v[200:201] neg_lo:[0,0,1] neg_hi:[0,0,1]
	v_pk_mul_f32 v[202:203], v[136:137], v[202:203]
	v_pk_mul_f32 v[204:205], v[134:135], v[204:205]
	v_pk_fma_f32 v[196:197], v[132:133], v[196:197], v[202:203]
	v_pk_fma_f32 v[198:199], v[130:131], v[198:199], v[204:205]
	v_pk_mul_f32 v[202:203], v[144:145], v[178:179]
	v_pk_mul_f32 v[204:205], v[142:143], v[192:193]
	v_pk_fma_f32 v[202:203], v[140:141], v[206:207], v[202:203] neg_lo:[0,0,1] neg_hi:[0,0,1]
	v_pk_fma_f32 v[204:205], v[138:139], v[208:209], v[204:205] neg_lo:[0,0,1] neg_hi:[0,0,1]
	v_pk_mul_f32 v[206:207], v[144:145], v[206:207]
	v_pk_mul_f32 v[208:209], v[142:143], v[208:209]
	v_pk_fma_f32 v[178:179], v[140:141], v[178:179], v[206:207]
	v_pk_fma_f32 v[192:193], v[138:139], v[192:193], v[208:209]
	v_pk_mul_f32 v[206:207], v[136:137], v[196:197]
	v_pk_mul_f32 v[208:209], v[134:135], v[198:199]
	v_pk_fma_f32 v[206:207], v[132:133], v[194:195], v[206:207] neg_lo:[0,0,1] neg_hi:[0,0,1]
	v_pk_fma_f32 v[208:209], v[130:131], v[200:201], v[208:209] neg_lo:[0,0,1] neg_hi:[0,0,1]
	v_pk_mul_f32 v[194:195], v[136:137], v[194:195]
	v_pk_mul_f32 v[200:201], v[134:135], v[200:201]
	v_pk_fma_f32 v[194:195], v[132:133], v[196:197], v[194:195]
	v_pk_fma_f32 v[196:197], v[130:131], v[198:199], v[200:201]
	v_pk_mul_f32 v[198:199], v[144:145], v[178:179]
	v_pk_mul_f32 v[200:201], v[142:143], v[192:193]
	v_pk_fma_f32 v[198:199], v[140:141], v[202:203], v[198:199] neg_lo:[0,0,1] neg_hi:[0,0,1]
	v_pk_fma_f32 v[200:201], v[138:139], v[204:205], v[200:201] neg_lo:[0,0,1] neg_hi:[0,0,1]
	v_pk_mul_f32 v[202:203], v[144:145], v[202:203]
	v_pk_mul_f32 v[204:205], v[142:143], v[204:205]
	v_pk_fma_f32 v[178:179], v[140:141], v[178:179], v[202:203]
	v_pk_fma_f32 v[192:193], v[138:139], v[192:193], v[204:205]
	v_pk_mul_f32 v[202:203], v[136:137], v[194:195]
	v_pk_mul_f32 v[204:205], v[134:135], v[196:197]
	v_pk_fma_f32 v[202:203], v[132:133], v[206:207], v[202:203] neg_lo:[0,0,1] neg_hi:[0,0,1]
	v_pk_fma_f32 v[204:205], v[130:131], v[208:209], v[204:205] neg_lo:[0,0,1] neg_hi:[0,0,1]
	v_pk_mul_f32 v[206:207], v[136:137], v[206:207]
	v_pk_mul_f32 v[208:209], v[134:135], v[208:209]
	v_pk_fma_f32 v[194:195], v[132:133], v[194:195], v[206:207]
	v_pk_fma_f32 v[196:197], v[130:131], v[196:197], v[208:209]
	v_pk_mul_f32 v[206:207], v[144:145], v[178:179]
	v_pk_mul_f32 v[208:209], v[142:143], v[192:193]
	v_pk_fma_f32 v[206:207], v[140:141], v[198:199], v[206:207] neg_lo:[0,0,1] neg_hi:[0,0,1]
	v_pk_fma_f32 v[208:209], v[138:139], v[200:201], v[208:209] neg_lo:[0,0,1] neg_hi:[0,0,1]
	v_pk_mul_f32 v[198:199], v[144:145], v[198:199]
	v_pk_mul_f32 v[200:201], v[142:143], v[200:201]
	v_pk_fma_f32 v[178:179], v[140:141], v[178:179], v[198:199]
	v_pk_fma_f32 v[198:199], v[138:139], v[192:193], v[200:201]
	v_pk_mul_f32 v[192:193], v[136:137], v[194:195]
; __device__ __forceinline__ unsigned cvt_pk_bf16(float lo, float hi) { unsigned r; asm volatile("v_cvt_pk_bf16_f32 %0, %1, %2" : "=v"(r) : "v"(lo), "v"(hi)); return r; }
;     __device__ __forceinline__ void operator()(const f32x4 (&acc)[2][2][4][2], const pg8::Unit& u, int wr, int wc, int fr, int fq) const {
;     ...
;             for (int k = 0; k < 12; ++k) {
;                 if (k < 4 || k >= 8) {
;                     const int ai = k >> 3, m = k & 3;
;                     const int row = row0 + ai * 128 + m * 16;
;                     const f32x4 c0 = c[0] * osc, c1 = c[1] * osc, s0 = sn[0] * osc, s1 = sn[1] * osc;
;                     const f32x4 a0 = acc[ai][0][m][0], a1 = acc[ai][0][m][1], b0 = acc[ai][1][m][0], b1 = acc[ai][1][m][1];
;                     const f32x4 o10 = a0 * c0 - b0 * s0, o11 = a1 * c1 - b1 * s1, o20 = a0 * s0 + b0 * c0, o21 = a1 * s1 + b1 * c1;
;                     bf16_t* rowp = base + (size_t)row * 512 + col0;
;                     u32x4 w; w.x = cvt_pk_bf16(o10[0], o10[1]); w.y = cvt_pk_bf16(o10[2], o10[3]); w.z = cvt_pk_bf16(o11[0], o11[1]); w.w = cvt_pk_bf16(o11[2], o11[3]);
;                     *(u32x4*)(rowp) = w;
;                     w.x = cvt_pk_bf16(o20[0], o20[1]); w.y = cvt_pk_bf16(o20[2], o20[3]); w.z = cvt_pk_bf16(o21[0], o21[1]); w.w = cvt_pk_bf16(o21[2], o21[3]);
;                     *(u32x4*)(rowp + 64) = w;
;                 }
;                 if (k < 11) {
; #pragma unroll
;                     for (int e = 0; e < 2; ++e) { const f32x4 cn = c[e] * c16[e] - sn[e] * s16[e]; sn[e] = sn[e] * c16[e] + c[e] * s16[e]; c[e] = cn; } }
	v_pk_mul_f32 v[200:201], v[134:135], v[196:197]
	v_pk_fma_f32 v[210:211], v[132:133], v[202:203], v[192:193] neg_lo:[0,0,1] neg_hi:[0,0,1]
	v_pk_mul_f32 v[192:193], v[136:137], v[202:203]
	v_pk_mul_f32 v[202:203], v[134:135], v[204:205]
	v_pk_mul_f32 v[216:217], v[176:177], v[198:199] op_sel_hi:[0,1]
	v_pk_fma_f32 v[200:201], v[130:131], v[204:205], v[200:201] neg_lo:[0,0,1] neg_hi:[0,0,1]
	v_pk_fma_f32 v[204:205], v[132:133], v[194:195], v[192:193]
	v_pk_fma_f32 v[196:197], v[130:131], v[196:197], v[202:203]
	v_pk_mul_f32 v[194:195], v[176:177], v[208:209] op_sel_hi:[0,1]
	v_pk_mul_f32 v[214:215], v[176:177], v[178:179] op_sel_hi:[0,1]
	v_pk_mul_f32 v[224:225], v[54:55], v[216:217]
	v_pk_mul_f32 v[192:193], v[176:177], v[206:207] op_sel_hi:[0,1]
	v_pk_mul_f32 v[212:213], v[176:177], v[200:201] op_sel_hi:[0,1]
	v_pk_mul_f32 v[220:221], v[176:177], v[196:197] op_sel_hi:[0,1]
	v_pk_mul_f32 v[222:223], v[56:57], v[214:215]
	v_pk_fma_f32 v[224:225], v[62:63], v[194:195], v[224:225] neg_lo:[0,0,1] neg_hi:[0,0,1]
	v_pk_mul_f32 v[194:195], v[54:55], v[194:195]
	v_pk_mul_f32 v[202:203], v[176:177], v[210:211] op_sel_hi:[0,1]
	v_pk_mul_f32 v[218:219], v[176:177], v[204:205] op_sel_hi:[0,1]
	v_pk_fma_f32 v[222:223], v[64:65], v[192:193], v[222:223] neg_lo:[0,0,1] neg_hi:[0,0,1]
	v_pk_mul_f32 v[228:229], v[50:51], v[220:221]
	v_pk_mul_f32 v[192:193], v[56:57], v[192:193]
	v_pk_fma_f32 v[216:217], v[62:63], v[216:217], v[194:195]
	v_pk_mul_f32 v[194:195], v[50:51], v[212:213]
	v_pk_mul_f32 v[226:227], v[52:53], v[218:219]
	v_pk_fma_f32 v[228:229], v[58:59], v[212:213], v[228:229] neg_lo:[0,0,1] neg_hi:[0,0,1]
	v_pk_fma_f32 v[214:215], v[64:65], v[214:215], v[192:193]
	v_pk_mul_f32 v[192:193], v[52:53], v[202:203]
	v_pk_fma_f32 v[212:213], v[58:59], v[220:221], v[194:195]
	v_add_co_u32_e32 v220, vcc, s87, v174
	v_pk_fma_f32 v[226:227], v[60:61], v[202:203], v[226:227] neg_lo:[0,0,1] neg_hi:[0,0,1]
	v_pk_fma_f32 v[202:203], v[60:61], v[218:219], v[192:193]
	v_cvt_pk_bf16_f32 v192, v224, v225
	v_cvt_pk_bf16_f32 v193, v222, v223
	v_cvt_pk_bf16_f32 v194, v228, v229
	v_cvt_pk_bf16_f32 v195, v226, v227
	v_addc_co_u32_e32 v221, vcc, 0, v175, vcc
	v_lshl_add_u64 v[218:219], v[174:175], 0, s[16:17]
	global_store_dwordx4 v[220:221], v[192:195], off sc1
	s_nop 1
	v_cvt_pk_bf16_f32 v192, v216, v217
	v_cvt_pk_bf16_f32 v193, v214, v215
	v_cvt_pk_bf16_f32 v194, v212, v213
	v_cvt_pk_bf16_f32 v195, v202, v203
	global_store_dwordx4 v[218:219], v[192:195], off offset:128 sc1
	s_nop 1
	v_pk_mul_f32 v[194:195], v[142:143], v[198:199]
	v_pk_mul_f32 v[192:193], v[144:145], v[178:179]
	v_pk_fma_f32 v[212:213], v[138:139], v[208:209], v[194:195] neg_lo:[0,0,1] neg_hi:[0,0,1]
	v_pk_mul_f32 v[194:195], v[142:143], v[208:209]
	v_pk_fma_f32 v[202:203], v[140:141], v[206:207], v[192:193] neg_lo:[0,0,1] neg_hi:[0,0,1]
	v_pk_mul_f32 v[192:193], v[144:145], v[206:207]
	v_pk_fma_f32 v[198:199], v[138:139], v[198:199], v[194:195]
	v_pk_mul_f32 v[194:195], v[134:135], v[196:197]
	v_pk_fma_f32 v[178:179], v[140:141], v[178:179], v[192:193]
	v_pk_mul_f32 v[192:193], v[136:137], v[204:205]
	v_pk_fma_f32 v[208:209], v[130:131], v[200:201], v[194:195] neg_lo:[0,0,1] neg_hi:[0,0,1]
	v_pk_mul_f32 v[194:195], v[134:135], v[200:201]
	v_pk_mul_f32 v[216:217], v[176:177], v[198:199] op_sel_hi:[0,1]
	v_pk_fma_f32 v[206:207], v[132:133], v[210:211], v[192:193] neg_lo:[0,0,1] neg_hi:[0,0,1]
	v_pk_mul_f32 v[192:193], v[136:137], v[210:211]
	v_pk_fma_f32 v[196:197], v[130:131], v[196:197], v[194:195]
	v_pk_mul_f32 v[194:195], v[176:177], v[212:213] op_sel_hi:[0,1]
	v_pk_mul_f32 v[214:215], v[176:177], v[178:179] op_sel_hi:[0,1]
	v_pk_mul_f32 v[224:225], v[38:39], v[216:217]
	v_pk_fma_f32 v[200:201], v[132:133], v[204:205], v[192:193]
	v_pk_mul_f32 v[192:193], v[176:177], v[202:203] op_sel_hi:[0,1]
	v_pk_mul_f32 v[210:211], v[176:177], v[208:209] op_sel_hi:[0,1]
	v_pk_mul_f32 v[220:221], v[176:177], v[196:197] op_sel_hi:[0,1]
	v_pk_mul_f32 v[222:223], v[40:41], v[214:215]
	v_pk_fma_f32 v[224:225], v[46:47], v[194:195], v[224:225] neg_lo:[0,0,1] neg_hi:[0,0,1]
	v_pk_mul_f32 v[194:195], v[38:39], v[194:195]
	v_pk_mul_f32 v[204:205], v[176:177], v[206:207] op_sel_hi:[0,1]
	v_pk_mul_f32 v[218:219], v[176:177], v[200:201] op_sel_hi:[0,1]
	v_pk_fma_f32 v[222:223], v[48:49], v[192:193], v[222:223] neg_lo:[0,0,1] neg_hi:[0,0,1]
	v_pk_mul_f32 v[228:229], v[34:35], v[220:221]
	v_pk_mul_f32 v[192:193], v[40:41], v[192:193]
	v_pk_fma_f32 v[216:217], v[46:47], v[216:217], v[194:195]
	v_pk_mul_f32 v[194:195], v[34:35], v[210:211]
	v_pk_mul_f32 v[226:227], v[36:37], v[218:219]
	v_pk_fma_f32 v[228:229], v[42:43], v[210:211], v[228:229] neg_lo:[0,0,1] neg_hi:[0,0,1]
	v_pk_fma_f32 v[214:215], v[48:49], v[214:215], v[192:193]
	v_pk_mul_f32 v[192:193], v[36:37], v[204:205]
	v_pk_fma_f32 v[210:211], v[42:43], v[220:221], v[194:195]
	v_add_co_u32_e32 v220, vcc, s88, v174
	v_pk_fma_f32 v[226:227], v[44:45], v[204:205], v[226:227] neg_lo:[0,0,1] neg_hi:[0,0,1]
	v_pk_fma_f32 v[204:205], v[44:45], v[218:219], v[192:193]
	v_cvt_pk_bf16_f32 v192, v224, v225
	v_cvt_pk_bf16_f32 v193, v222, v223
	v_cvt_pk_bf16_f32 v194, v228, v229
	v_cvt_pk_bf16_f32 v195, v226, v227
	v_addc_co_u32_e32 v221, vcc, 0, v175, vcc
	v_lshl_add_u64 v[218:219], v[174:175], 0, s[18:19]
	global_store_dwordx4 v[220:221], v[192:195], off sc1
	s_nop 1
	v_cvt_pk_bf16_f32 v192, v216, v217
	v_cvt_pk_bf16_f32 v193, v214, v215
	v_cvt_pk_bf16_f32 v194, v210, v211
	v_cvt_pk_bf16_f32 v195, v204, v205
	global_store_dwordx4 v[218:219], v[192:195], off offset:128 sc1
	s_nop 1
	v_pk_mul_f32 v[194:195], v[142:143], v[198:199]
	v_pk_mul_f32 v[192:193], v[144:145], v[178:179]
; __device__ __forceinline__ unsigned cvt_pk_bf16(float lo, float hi) { unsigned r; asm volatile("v_cvt_pk_bf16_f32 %0, %1, %2" : "=v"(r) : "v"(lo), "v"(hi)); return r; }
;     __device__ __forceinline__ void operator()(const f32x4 (&acc)[2][2][4][2], const pg8::Unit& u, int wr, int wc, int fr, int fq) const {
;     ...
;             for (int k = 0; k < 12; ++k) {
;                 if (k < 4 || k >= 8) {
;                     const int ai = k >> 3, m = k & 3;
;                     const int row = row0 + ai * 128 + m * 16;
;                     const f32x4 c0 = c[0] * osc, c1 = c[1] * osc, s0 = sn[0] * osc, s1 = sn[1] * osc;
;                     const f32x4 a0 = acc[ai][0][m][0], a1 = acc[ai][0][m][1], b0 = acc[ai][1][m][0], b1 = acc[ai][1][m][1];
;                     const f32x4 o10 = a0 * c0 - b0 * s0, o11 = a1 * c1 - b1 * s1, o20 = a0 * s0 + b0 * c0, o21 = a1 * s1 + b1 * c1;
;                     bf16_t* rowp = base + (size_t)row * 512 + col0;
;                     u32x4 w; w.x = cvt_pk_bf16(o10[0], o10[1]); w.y = cvt_pk_bf16(o10[2], o10[3]); w.z = cvt_pk_bf16(o11[0], o11[1]); w.w = cvt_pk_bf16(o11[2], o11[3]);
;                     *(u32x4*)(rowp) = w;
;                     w.x = cvt_pk_bf16(o20[0], o20[1]); w.y = cvt_pk_bf16(o20[2], o20[3]); w.z = cvt_pk_bf16(o21[0], o21[1]); w.w = cvt_pk_bf16(o21[2], o21[3]);
;                     *(u32x4*)(rowp + 64) = w;
;                 }
;                 if (k < 11) {
; #pragma unroll
;                     for (int e = 0; e < 2; ++e) { const f32x4 cn = c[e] * c16[e] - sn[e] * s16[e]; sn[e] = sn[e] * c16[e] + c[e] * s16[e]; c[e] = cn; } }
	v_pk_fma_f32 v[210:211], v[138:139], v[212:213], v[194:195] neg_lo:[0,0,1] neg_hi:[0,0,1]
	v_pk_mul_f32 v[194:195], v[142:143], v[212:213]
	v_pk_fma_f32 v[204:205], v[140:141], v[202:203], v[192:193] neg_lo:[0,0,1] neg_hi:[0,0,1]
	v_pk_mul_f32 v[192:193], v[144:145], v[202:203]
	v_pk_fma_f32 v[198:199], v[138:139], v[198:199], v[194:195]
	v_pk_mul_f32 v[194:195], v[134:135], v[196:197]
	v_pk_fma_f32 v[178:179], v[140:141], v[178:179], v[192:193]
	v_pk_mul_f32 v[192:193], v[136:137], v[200:201]
	v_pk_fma_f32 v[212:213], v[130:131], v[208:209], v[194:195] neg_lo:[0,0,1] neg_hi:[0,0,1]
	v_pk_mul_f32 v[194:195], v[134:135], v[208:209]
	v_pk_mul_f32 v[216:217], v[176:177], v[198:199] op_sel_hi:[0,1]
	v_pk_fma_f32 v[202:203], v[132:133], v[206:207], v[192:193] neg_lo:[0,0,1] neg_hi:[0,0,1]
	v_pk_mul_f32 v[192:193], v[136:137], v[206:207]
	v_pk_fma_f32 v[196:197], v[130:131], v[196:197], v[194:195]
	v_pk_mul_f32 v[194:195], v[176:177], v[210:211] op_sel_hi:[0,1]
	v_pk_mul_f32 v[214:215], v[176:177], v[178:179] op_sel_hi:[0,1]
	v_pk_mul_f32 v[224:225], v[22:23], v[216:217]
	v_pk_fma_f32 v[200:201], v[132:133], v[200:201], v[192:193]
	v_pk_mul_f32 v[192:193], v[176:177], v[204:205] op_sel_hi:[0,1]
	v_pk_mul_f32 v[208:209], v[176:177], v[212:213] op_sel_hi:[0,1]
	v_pk_mul_f32 v[220:221], v[176:177], v[196:197] op_sel_hi:[0,1]
	v_pk_mul_f32 v[222:223], v[24:25], v[214:215]
	v_pk_fma_f32 v[224:225], v[30:31], v[194:195], v[224:225] neg_lo:[0,0,1] neg_hi:[0,0,1]
	v_pk_mul_f32 v[194:195], v[22:23], v[194:195]
	v_pk_mul_f32 v[206:207], v[176:177], v[202:203] op_sel_hi:[0,1]
	v_pk_mul_f32 v[218:219], v[176:177], v[200:201] op_sel_hi:[0,1]
	v_pk_fma_f32 v[222:223], v[32:33], v[192:193], v[222:223] neg_lo:[0,0,1] neg_hi:[0,0,1]
	v_pk_mul_f32 v[228:229], v[18:19], v[220:221]
	v_pk_mul_f32 v[192:193], v[24:25], v[192:193]
	v_pk_fma_f32 v[216:217], v[30:31], v[216:217], v[194:195]
	v_pk_mul_f32 v[194:195], v[18:19], v[208:209]
	v_pk_mul_f32 v[226:227], v[20:21], v[218:219]
	v_pk_fma_f32 v[228:229], v[26:27], v[208:209], v[228:229] neg_lo:[0,0,1] neg_hi:[0,0,1]
	v_pk_fma_f32 v[214:215], v[32:33], v[214:215], v[192:193]
	v_pk_mul_f32 v[192:193], v[20:21], v[206:207]
	v_pk_fma_f32 v[208:209], v[26:27], v[220:221], v[194:195]
	v_add_co_u32_e32 v220, vcc, s89, v174
	v_pk_fma_f32 v[226:227], v[28:29], v[206:207], v[226:227] neg_lo:[0,0,1] neg_hi:[0,0,1]
	v_pk_fma_f32 v[206:207], v[28:29], v[218:219], v[192:193]
	v_cvt_pk_bf16_f32 v192, v224, v225
	v_cvt_pk_bf16_f32 v193, v222, v223
	v_cvt_pk_bf16_f32 v194, v228, v229
	v_cvt_pk_bf16_f32 v195, v226, v227
	v_addc_co_u32_e32 v221, vcc, 0, v175, vcc
	v_lshl_add_u64 v[218:219], v[174:175], 0, s[20:21]
	global_store_dwordx4 v[220:221], v[192:195], off sc1
	s_nop 1
	v_cvt_pk_bf16_f32 v192, v216, v217
	v_cvt_pk_bf16_f32 v193, v214, v215
	v_cvt_pk_bf16_f32 v194, v208, v209
	v_cvt_pk_bf16_f32 v195, v206, v207
	global_store_dwordx4 v[218:219], v[192:195], off offset:128 sc1
	s_nop 1
	v_pk_mul_f32 v[192:193], v[144:145], v[178:179]
	v_pk_mul_f32 v[194:195], v[142:143], v[198:199]
	v_pk_mul_f32 v[144:145], v[144:145], v[204:205]
	v_pk_mul_f32 v[142:143], v[142:143], v[210:211]
	v_pk_fma_f32 v[192:193], v[140:141], v[204:205], v[192:193] neg_lo:[0,0,1] neg_hi:[0,0,1]
	v_pk_fma_f32 v[194:195], v[138:139], v[210:211], v[194:195] neg_lo:[0,0,1] neg_hi:[0,0,1]
	v_pk_fma_f32 v[140:141], v[140:141], v[178:179], v[144:145]
	v_pk_fma_f32 v[138:139], v[138:139], v[198:199], v[142:143]
	v_pk_mul_f32 v[142:143], v[136:137], v[200:201]
	v_pk_mul_f32 v[144:145], v[134:135], v[196:197]
	v_pk_mul_f32 v[136:137], v[136:137], v[202:203]
	v_pk_mul_f32 v[134:135], v[134:135], v[212:213]
	v_pk_fma_f32 v[142:143], v[132:133], v[202:203], v[142:143] neg_lo:[0,0,1] neg_hi:[0,0,1]
	v_pk_fma_f32 v[144:145], v[130:131], v[212:213], v[144:145] neg_lo:[0,0,1] neg_hi:[0,0,1]
	v_pk_fma_f32 v[132:133], v[132:133], v[200:201], v[136:137]
	v_pk_fma_f32 v[130:131], v[130:131], v[196:197], v[134:135]
	v_pk_mul_f32 v[140:141], v[176:177], v[140:141] op_sel_hi:[0,1]
	v_pk_mul_f32 v[138:139], v[176:177], v[138:139] op_sel_hi:[0,1]
	v_pk_mul_f32 v[134:135], v[176:177], v[192:193] op_sel_hi:[0,1]
	v_pk_mul_f32 v[136:137], v[176:177], v[194:195] op_sel_hi:[0,1]
	v_pk_mul_f32 v[142:143], v[176:177], v[142:143] op_sel_hi:[0,1]
	v_pk_mul_f32 v[144:145], v[176:177], v[144:145] op_sel_hi:[0,1]
	v_pk_mul_f32 v[132:133], v[176:177], v[132:133] op_sel_hi:[0,1]
	v_pk_mul_f32 v[130:131], v[176:177], v[130:131] op_sel_hi:[0,1]
	v_pk_mul_f32 v[176:177], v[8:9], v[140:141]
	v_pk_mul_f32 v[178:179], v[6:7], v[138:139]
	v_pk_fma_f32 v[176:177], v[16:17], v[134:135], v[176:177] neg_lo:[0,0,1] neg_hi:[0,0,1]
	v_pk_fma_f32 v[178:179], v[14:15], v[136:137], v[178:179] neg_lo:[0,0,1] neg_hi:[0,0,1]
	v_pk_mul_f32 v[194:195], v[2:3], v[130:131]
	v_pk_mul_f32 v[134:135], v[8:9], v[134:135]
	v_pk_mul_f32 v[136:137], v[6:7], v[136:137]
	v_pk_mul_f32 v[192:193], v[4:5], v[132:133]
	v_pk_fma_f32 v[194:195], v[10:11], v[144:145], v[194:195] neg_lo:[0,0,1] neg_hi:[0,0,1]
	v_pk_fma_f32 v[134:135], v[16:17], v[140:141], v[134:135]
	v_pk_fma_f32 v[136:137], v[14:15], v[138:139], v[136:137]
	v_pk_mul_f32 v[138:139], v[4:5], v[142:143]
	v_pk_mul_f32 v[140:141], v[2:3], v[144:145]
	v_add_co_u32_e32 v144, vcc, s90, v174
	v_pk_fma_f32 v[192:193], v[12:13], v[142:143], v[192:193] neg_lo:[0,0,1] neg_hi:[0,0,1]
	v_pk_fma_f32 v[138:139], v[12:13], v[132:133], v[138:139]
	v_pk_fma_f32 v[140:141], v[10:11], v[130:131], v[140:141]
	v_lshl_add_u64 v[142:143], v[174:175], 0, s[24:25]
	v_cvt_pk_bf16_f32 v130, v178, v179
	v_cvt_pk_bf16_f32 v131, v176, v177
	v_cvt_pk_bf16_f32 v132, v194, v195
	v_cvt_pk_bf16_f32 v133, v192, v193
	v_addc_co_u32_e32 v145, vcc, 0, v175, vcc
	global_store_dwordx4 v[144:145], v[130:133], off sc1
	s_nop 1
	v_cvt_pk_bf16_f32 v130, v136, v137
	v_cvt_pk_bf16_f32 v131, v134, v135
	v_cvt_pk_bf16_f32 v132, v140, v141
	v_cvt_pk_bf16_f32 v133, v138, v139
	global_store_dwordx4 v[142:143], v[130:133], off offset:128 sc1

; __device__ __forceinline__ unsigned cvt_pk_bf16(float lo, float hi) { unsigned r; asm volatile("v_cvt_pk_bf16_f32 %0, %1, %2" : "=v"(r) : "v"(lo), "v"(hi)); return r; }
;     __device__ __forceinline__ void operator()(const f32x4 (&acc)[2][2][4][2], const pg8::Unit& u, int wr, int wc, int fr, int fq) const {
;     ...
;         if (sec <= 1) {
;             const float* gn = sec == 0 ? qg : kg; const float osc = sec == 0 ? 0.125f * LOG2E : 1.f;
;             f32x4 g[2][2];
; #pragma unroll
;             for (int bj = 0; bj < 2; ++bj)
; #pragma unroll
;                 for (int n = 0; n < 2; ++n) g[bj][n] = *(const f32x4*)(gn + 32 * bj + 8 * fq + 4 * n);
;             const int col0 = 256 * half + 64 * wc + 8 * fq;
; #pragma unroll
;             for (int ai = 0; ai < 2; ++ai)
; #pragma unroll
;                 for (int m = 0; m < 4; ++m) {
;                     float ss = 0.f;
; #pragma unroll
;                     for (int bj = 0; bj < 2; ++bj)
; #pragma unroll
;                         for (int n = 0; n < 2; ++n) { const f32x4 x = acc[ai][bj][m][n]; ss += (x[0] * x[0] + x[1] * x[1]) + (x[2] * x[2] + x[3] * x[3]); }
;                     ss = row4_sum(ss);
;                     const float r = rsqrtf(ss * (1.f / 64.f) + EPS) * osc;
;                     bf16_t* rowp = base + (size_t)(row0 + ai * 128 + m * 16) * 512 + col0;
; #pragma unroll
;                     for (int bj = 0; bj < 2; ++bj) { const f32x4 v0 = acc[ai][bj][m][0] * r * g[bj][0], v1 = acc[ai][bj][m][1] * r * g[bj][1];
;                         u32x4 w; w.x = cvt_pk_bf16(v0[0], v0[1]); w.y = cvt_pk_bf16(v0[2], v0[3]); w.z = cvt_pk_bf16(v1[0], v1[1]); w.w = cvt_pk_bf16(v1[2], v1[3]);
;                         *(u32x4*)(rowp + 32 * bj) = w; }
;                 }
.LBB0_205:
	s_cmp_lt_u32 s46, 2
	s_cselect_b64 vcc, -1, 0
	s_and_b64 s[4:5], vcc, exec
	s_cselect_b32 s5, s53, s55
	s_cselect_b32 s4, s52, s54
	global_load_dwordx4 v[142:145], v187, s[4:5]
	global_load_dwordx4 v[138:141], v187, s[4:5] offset:16
	global_load_dwordx4 v[134:137], v187, s[4:5] offset:128
	global_load_dwordx4 v[130:133], v187, s[4:5] offset:144
	v_mul_f32_e32 v176, v127, v127
	v_mul_f32_e32 v177, v129, v129
	v_mul_f32_e32 v179, v123, v123
	v_mul_f32_e32 v191, v125, v125
	v_mul_f32_e32 v192, v119, v119
	v_mul_f32_e32 v193, v121, v121
	v_ashrrev_i32_e32 v173, 31, v172
	v_fmac_f32_e32 v176, v126, v126
	v_fmac_f32_e32 v177, v128, v128
	v_fmac_f32_e32 v179, v122, v122
	v_fmac_f32_e32 v191, v124, v124
	v_mul_f32_e32 v194, v115, v115
	v_mul_f32_e32 v195, v117, v117
	v_fmac_f32_e32 v192, v118, v118
	v_fmac_f32_e32 v193, v120, v120
	v_lshlrev_b64 v[174:175], 10, v[172:173]
	v_add_f32_e32 v173, v176, v177
	v_add_f32_e32 v176, v179, v191
	v_fmac_f32_e32 v194, v114, v114
	v_fmac_f32_e32 v195, v116, v116
	v_add_f32_e32 v177, v192, v193
	v_add_f32_e32 v173, v173, v176
	v_add_f32_e32 v179, v194, v195
	v_add_f32_e32 v173, v173, v177
	v_add_f32_e32 v173, v173, v179
	v_mov_b32_e32 v176, v173
	s_nop 1
	v_permlane16_swap_b32_e32 v173, v176
	v_add_f32_e32 v173, v173, v176
	v_mov_b32_e32 v176, v173
	s_nop 1
	v_permlane32_swap_b32_e32 v173, v176
	v_add_f32_e32 v173, v173, v176
	v_fmamk_f32 v173, v173, 0x3c800000, v188
	v_cndmask_b32_e32 v178, 1.0, v190, vcc
	v_mul_f32_e32 v176, 0x4b800000, v173
	v_cmp_gt_f32_e32 vcc, s91, v173
	v_lshlrev_b32_e32 v154, 1, v182
	v_lshl_or_b32 v154, s27, 9, v154
	v_cndmask_b32_e32 v173, v173, v176, vcc
	v_rsq_f32_e32 v173, v173
	v_lshl_add_u64 v[176:177], s[48:49], 0, v[154:155]
	v_mul_f32_e32 v196, v111, v111
	v_mul_f32_e32 v197, v113, v113
	v_mul_f32_e32 v154, 0x45800000, v173
	v_cndmask_b32_e32 v154, v173, v154, vcc
	v_mul_f32_e32 v154, v178, v154
	v_pk_mul_f32 v[126:127], v[126:127], v[154:155] op_sel_hi:[1,0]
	v_pk_mul_f32 v[128:129], v[128:129], v[154:155] op_sel_hi:[1,0]
	v_pk_mul_f32 v[122:123], v[122:123], v[154:155] op_sel_hi:[1,0]
	v_pk_mul_f32 v[124:125], v[124:125], v[154:155] op_sel_hi:[1,0]
	v_pk_mul_f32 v[118:119], v[118:119], v[154:155] op_sel_hi:[1,0]
	v_pk_mul_f32 v[114:115], v[114:115], v[154:155] op_sel_hi:[1,0]
	v_pk_mul_f32 v[116:117], v[116:117], v[154:155] op_sel_hi:[1,0]
	v_mul_f32_e32 v198, v107, v107
	v_mul_f32_e32 v199, v109, v109
	v_lshl_add_u64 v[174:175], v[176:177], 0, v[174:175]
	v_fmac_f32_e32 v196, v110, v110
	v_fmac_f32_e32 v197, v112, v112
	v_fmac_f32_e32 v198, v106, v106
	v_fmac_f32_e32 v199, v108, v108
	v_add_f32_e32 v179, v196, v197
	v_pk_mul_f32 v[120:121], v[120:121], v[154:155] op_sel_hi:[1,0]
	s_waitcnt vmcnt(0)
	v_pk_mul_f32 v[128:129], v[144:145], v[128:129]
	v_pk_mul_f32 v[126:127], v[142:143], v[126:127]
	v_pk_mul_f32 v[124:125], v[140:141], v[124:125]
	v_pk_mul_f32 v[122:123], v[138:139], v[122:123]
	v_pk_mul_f32 v[118:119], v[134:135], v[118:119]
	v_pk_mul_f32 v[192:193], v[132:133], v[116:117]
	v_pk_mul_f32 v[194:195], v[130:131], v[114:115]
	v_cvt_pk_bf16_f32 v114, v126, v127
	v_cvt_pk_bf16_f32 v115, v128, v129
	v_cvt_pk_bf16_f32 v116, v122, v123
	v_cvt_pk_bf16_f32 v117, v124, v125
	global_store_dwordx4 v[174:175], v[114:117], off sc1
	v_pk_mul_f32 v[120:121], v[136:137], v[120:121]
	s_nop 0
	v_cvt_pk_bf16_f32 v114, v118, v119
	v_mul_f32_e32 v117, v103, v103
	v_mul_f32_e32 v118, v105, v105
	v_add_f32_e32 v116, v198, v199
	v_fmac_f32_e32 v117, v102, v102
	v_fmac_f32_e32 v118, v104, v104
	v_add_f32_e32 v116, v179, v116
	v_add_f32_e32 v117, v117, v118
	v_add_f32_e32 v116, v116, v117
	v_mul_f32_e32 v117, v99, v99
	v_mul_f32_e32 v118, v101, v101
	v_fmac_f32_e32 v117, v98, v98
	v_fmac_f32_e32 v118, v100, v100
	v_add_f32_e32 v117, v117, v118
	v_add_f32_e32 v116, v116, v117
	v_mov_b32_e32 v117, v116
	s_nop 1
	v_permlane16_swap_b32_e32 v116, v117
	v_add_f32_e32 v116, v116, v117
	v_mov_b32_e32 v117, v116
	s_nop 1
	v_permlane32_swap_b32_e32 v116, v117
	v_add_f32_e32 v116, v116, v117
	v_fmamk_f32 v116, v116, 0x3c800000, v188
	v_mul_f32_e32 v117, 0x4b800000, v116
	v_cmp_gt_f32_e32 vcc, s91, v116
	v_cvt_pk_bf16_f32 v115, v120, v121
	s_nop 1
	v_cndmask_b32_e32 v116, v116, v117, vcc
	v_rsq_f32_e32 v118, v116
	v_cvt_pk_bf16_f32 v116, v194, v195
	v_cvt_pk_bf16_f32 v117, v192, v193
	global_store_dwordx4 v[174:175], v[114:117], off offset:64 sc1
	s_nop 1
	v_mul_f32_e32 v114, 0x45800000, v118
	v_cndmask_b32_e32 v114, v118, v114, vcc
	v_or_b32_e32 v116, 16, v172
	v_mul_f32_e32 v114, v178, v114
	v_ashrrev_i32_e32 v117, 31, v116
	v_lshlrev_b64 v[116:117], 10, v[116:117]
	v_pk_mul_f32 v[110:111], v[110:111], v[114:115] op_sel_hi:[1,0]
	v_pk_mul_f32 v[112:113], v[112:113], v[114:115] op_sel_hi:[1,0]
	v_pk_mul_f32 v[106:107], v[106:107], v[114:115] op_sel_hi:[1,0]
	v_pk_mul_f32 v[108:109], v[108:109], v[114:115] op_sel_hi:[1,0]
	v_pk_mul_f32 v[102:103], v[102:103], v[114:115] op_sel_hi:[1,0]
	v_lshl_add_u64 v[116:117], v[176:177], 0, v[116:117]
	v_pk_mul_f32 v[112:113], v[144:145], v[112:113]
	v_pk_mul_f32 v[110:111], v[142:143], v[110:111]
	v_pk_mul_f32 v[118:119], v[140:141], v[108:109]
	v_pk_mul_f32 v[108:109], v[138:139], v[106:107]
	v_cvt_pk_bf16_f32 v106, v110, v111
	v_cvt_pk_bf16_f32 v107, v112, v113
	v_pk_mul_f32 v[102:103], v[134:135], v[102:103]
	v_pk_mul_f32 v[98:99], v[98:99], v[114:115] op_sel_hi:[1,0]
	v_pk_mul_f32 v[100:101], v[100:101], v[114:115] op_sel_hi:[1,0]
	v_cvt_pk_bf16_f32 v108, v108, v109
	v_cvt_pk_bf16_f32 v109, v118, v119
	global_store_dwordx4 v[116:117], v[106:109], off sc1
	v_pk_mul_f32 v[104:105], v[104:105], v[114:115] op_sel_hi:[1,0]
	s_nop 0
; __device__ __forceinline__ unsigned cvt_pk_bf16(float lo, float hi) { unsigned r; asm volatile("v_cvt_pk_bf16_f32 %0, %1, %2" : "=v"(r) : "v"(lo), "v"(hi)); return r; }
;     __device__ __forceinline__ void operator()(const f32x4 (&acc)[2][2][4][2], const pg8::Unit& u, int wr, int wc, int fr, int fq) const {
;     ...
;                 for (int m = 0; m < 4; ++m) {
;                     float ss = 0.f;
; #pragma unroll
;                     for (int bj = 0; bj < 2; ++bj)
; #pragma unroll
;                         for (int n = 0; n < 2; ++n) { const f32x4 x = acc[ai][bj][m][n]; ss += (x[0] * x[0] + x[1] * x[1]) + (x[2] * x[2] + x[3] * x[3]); }
;                     ss = row4_sum(ss);
;                     const float r = rsqrtf(ss * (1.f / 64.f) + EPS) * osc;
;                     bf16_t* rowp = base + (size_t)(row0 + ai * 128 + m * 16) * 512 + col0;
; #pragma unroll
;                     for (int bj = 0; bj < 2; ++bj) { const f32x4 v0 = acc[ai][bj][m][0] * r * g[bj][0], v1 = acc[ai][bj][m][1] * r * g[bj][1];
;                         u32x4 w; w.x = cvt_pk_bf16(v0[0], v0[1]); w.y = cvt_pk_bf16(v0[2], v0[3]); w.z = cvt_pk_bf16(v1[0], v1[1]); w.w = cvt_pk_bf16(v1[2], v1[3]);
;                         *(u32x4*)(rowp + 32 * bj) = w; }
;                 }
	v_pk_mul_f32 v[106:107], v[132:133], v[100:101]
	v_pk_mul_f32 v[100:101], v[130:131], v[98:99]
	v_cvt_pk_bf16_f32 v98, v102, v103
	v_mul_f32_e32 v102, v95, v95
	v_mul_f32_e32 v103, v97, v97
	v_pk_mul_f32 v[104:105], v[136:137], v[104:105]
	v_fmac_f32_e32 v102, v94, v94
	v_fmac_f32_e32 v103, v96, v96
	v_cvt_pk_bf16_f32 v99, v104, v105
	v_add_f32_e32 v102, v102, v103
	v_mul_f32_e32 v103, v91, v91
	v_mul_f32_e32 v104, v93, v93
	v_fmac_f32_e32 v103, v90, v90
	v_fmac_f32_e32 v104, v92, v92
	v_add_f32_e32 v103, v103, v104
	v_add_f32_e32 v102, v102, v103
	v_mul_f32_e32 v103, v87, v87
	v_mul_f32_e32 v104, v89, v89
	v_fmac_f32_e32 v103, v86, v86
	v_fmac_f32_e32 v104, v88, v88
	v_add_f32_e32 v103, v103, v104
	v_add_f32_e32 v102, v102, v103
	v_mul_f32_e32 v103, v83, v83
	v_mul_f32_e32 v104, v85, v85
	v_fmac_f32_e32 v103, v82, v82
	v_fmac_f32_e32 v104, v84, v84
	v_add_f32_e32 v103, v103, v104
	v_add_f32_e32 v102, v102, v103
	v_mov_b32_e32 v103, v102
	s_nop 1
	v_permlane16_swap_b32_e32 v102, v103
	v_add_f32_e32 v102, v102, v103
	v_mov_b32_e32 v103, v102
	s_nop 1
	v_permlane32_swap_b32_e32 v102, v103
	v_add_f32_e32 v102, v102, v103
	v_fmamk_f32 v102, v102, 0x3c800000, v188
	v_mul_f32_e32 v103, 0x4b800000, v102
	v_cmp_gt_f32_e32 vcc, s91, v102
	v_cvt_pk_bf16_f32 v100, v100, v101
	v_cvt_pk_bf16_f32 v101, v106, v107
	global_store_dwordx4 v[116:117], v[98:101], off offset:64 sc1
	s_nop 0
	v_cndmask_b32_e32 v102, v102, v103, vcc
	v_rsq_f32_e32 v102, v102
	v_or_b32_e32 v100, 32, v172
	v_ashrrev_i32_e32 v101, 31, v100
	v_lshlrev_b64 v[100:101], 10, v[100:101]
	v_mul_f32_e32 v98, 0x45800000, v102
	v_cndmask_b32_e32 v98, v102, v98, vcc
	v_mul_f32_e32 v98, v178, v98
	v_pk_mul_f32 v[94:95], v[94:95], v[98:99] op_sel_hi:[1,0]
	v_pk_mul_f32 v[96:97], v[96:97], v[98:99] op_sel_hi:[1,0]
	v_pk_mul_f32 v[90:91], v[90:91], v[98:99] op_sel_hi:[1,0]
	v_pk_mul_f32 v[92:93], v[92:93], v[98:99] op_sel_hi:[1,0]
	v_pk_mul_f32 v[86:87], v[86:87], v[98:99] op_sel_hi:[1,0]
	v_lshl_add_u64 v[100:101], v[176:177], 0, v[100:101]
	v_pk_mul_f32 v[96:97], v[144:145], v[96:97]
	v_pk_mul_f32 v[94:95], v[142:143], v[94:95]
	v_pk_mul_f32 v[102:103], v[140:141], v[92:93]
	v_pk_mul_f32 v[92:93], v[138:139], v[90:91]
	v_cvt_pk_bf16_f32 v90, v94, v95
	v_cvt_pk_bf16_f32 v91, v96, v97
	v_pk_mul_f32 v[86:87], v[134:135], v[86:87]
	v_pk_mul_f32 v[82:83], v[82:83], v[98:99] op_sel_hi:[1,0]
	v_pk_mul_f32 v[84:85], v[84:85], v[98:99] op_sel_hi:[1,0]
	v_cvt_pk_bf16_f32 v92, v92, v93
	v_cvt_pk_bf16_f32 v93, v102, v103
	global_store_dwordx4 v[100:101], v[90:93], off sc1
	v_pk_mul_f32 v[88:89], v[88:89], v[98:99] op_sel_hi:[1,0]
	s_nop 0
	v_pk_mul_f32 v[90:91], v[132:133], v[84:85]
	v_pk_mul_f32 v[84:85], v[130:131], v[82:83]
	v_cvt_pk_bf16_f32 v82, v86, v87
	v_mul_f32_e32 v86, v79, v79
	v_mul_f32_e32 v87, v81, v81
	v_pk_mul_f32 v[88:89], v[136:137], v[88:89]
	v_fmac_f32_e32 v86, v78, v78
	v_fmac_f32_e32 v87, v80, v80
	v_cvt_pk_bf16_f32 v83, v88, v89
	v_add_f32_e32 v86, v86, v87
	v_mul_f32_e32 v87, v75, v75
	v_mul_f32_e32 v88, v77, v77
	v_fmac_f32_e32 v87, v74, v74
	v_fmac_f32_e32 v88, v76, v76
	v_add_f32_e32 v87, v87, v88
	v_add_f32_e32 v86, v86, v87
	v_mul_f32_e32 v87, v71, v71
	v_mul_f32_e32 v88, v73, v73
	v_fmac_f32_e32 v87, v70, v70
	v_fmac_f32_e32 v88, v72, v72
	v_add_f32_e32 v87, v87, v88
	v_add_f32_e32 v86, v86, v87
	v_mul_f32_e32 v87, v67, v67
	v_mul_f32_e32 v88, v69, v69
	v_fmac_f32_e32 v87, v66, v66
	v_fmac_f32_e32 v88, v68, v68
	v_add_f32_e32 v87, v87, v88
	v_add_f32_e32 v86, v86, v87
	v_mov_b32_e32 v87, v86
	s_nop 1
	v_permlane16_swap_b32_e32 v86, v87
	v_add_f32_e32 v86, v86, v87
	v_mov_b32_e32 v87, v86
	s_nop 1
	v_permlane32_swap_b32_e32 v86, v87
	v_add_f32_e32 v86, v86, v87
	v_fmamk_f32 v86, v86, 0x3c800000, v188
	v_mul_f32_e32 v87, 0x4b800000, v86
	v_cmp_gt_f32_e32 vcc, s91, v86
	v_cvt_pk_bf16_f32 v84, v84, v85
	v_cvt_pk_bf16_f32 v85, v90, v91
	global_store_dwordx4 v[100:101], v[82:85], off offset:64 sc1
	s_nop 0
	v_cndmask_b32_e32 v86, v86, v87, vcc
	v_rsq_f32_e32 v86, v86
	v_or_b32_e32 v84, 48, v172
	v_ashrrev_i32_e32 v85, 31, v84
	v_lshlrev_b64 v[84:85], 10, v[84:85]
	v_mul_f32_e32 v82, 0x45800000, v86
	v_cndmask_b32_e32 v82, v86, v82, vcc
	v_mul_f32_e32 v82, v178, v82
	v_pk_mul_f32 v[78:79], v[78:79], v[82:83] op_sel_hi:[1,0]
	v_pk_mul_f32 v[80:81], v[80:81], v[82:83] op_sel_hi:[1,0]
	v_pk_mul_f32 v[74:75], v[74:75], v[82:83] op_sel_hi:[1,0]
	v_pk_mul_f32 v[76:77], v[76:77], v[82:83] op_sel_hi:[1,0]
	v_pk_mul_f32 v[70:71], v[70:71], v[82:83] op_sel_hi:[1,0]
	v_lshl_add_u64 v[84:85], v[176:177], 0, v[84:85]
	v_pk_mul_f32 v[80:81], v[144:145], v[80:81]
	v_pk_mul_f32 v[78:79], v[142:143], v[78:79]
	v_pk_mul_f32 v[86:87], v[140:141], v[76:77]
	v_pk_mul_f32 v[76:77], v[138:139], v[74:75]
	v_cvt_pk_bf16_f32 v74, v78, v79
	v_cvt_pk_bf16_f32 v75, v80, v81
	v_pk_mul_f32 v[70:71], v[134:135], v[70:71]
	v_pk_mul_f32 v[66:67], v[66:67], v[82:83] op_sel_hi:[1,0]
	v_pk_mul_f32 v[68:69], v[68:69], v[82:83] op_sel_hi:[1,0]
	v_cvt_pk_bf16_f32 v76, v76, v77
	v_cvt_pk_bf16_f32 v77, v86, v87
	global_store_dwordx4 v[84:85], v[74:77], off sc1
	v_pk_mul_f32 v[72:73], v[72:73], v[82:83] op_sel_hi:[1,0]
	s_nop 0
	v_pk_mul_f32 v[74:75], v[132:133], v[68:69]
	v_pk_mul_f32 v[68:69], v[130:131], v[66:67]
	v_cvt_pk_bf16_f32 v66, v70, v71
	v_mul_f32_e32 v70, v63, v63
	v_mul_f32_e32 v71, v65, v65
	v_pk_mul_f32 v[72:73], v[136:137], v[72:73]
	v_fmac_f32_e32 v70, v62, v62
	v_fmac_f32_e32 v71, v64, v64
	v_cvt_pk_bf16_f32 v67, v72, v73
	v_add_f32_e32 v70, v70, v71
	v_mul_f32_e32 v71, v59, v59
	v_mul_f32_e32 v72, v61, v61
	v_fmac_f32_e32 v71, v58, v58
	v_fmac_f32_e32 v72, v60, v60
	v_add_f32_e32 v71, v71, v72
; __device__ __forceinline__ unsigned cvt_pk_bf16(float lo, float hi) { unsigned r; asm volatile("v_cvt_pk_bf16_f32 %0, %1, %2" : "=v"(r) : "v"(lo), "v"(hi)); return r; }
;     __device__ __forceinline__ void operator()(const f32x4 (&acc)[2][2][4][2], const pg8::Unit& u, int wr, int wc, int fr, int fq) const {
;     ...
;                 for (int m = 0; m < 4; ++m) {
;                     float ss = 0.f;
; #pragma unroll
;                     for (int bj = 0; bj < 2; ++bj)
; #pragma unroll
;                         for (int n = 0; n < 2; ++n) { const f32x4 x = acc[ai][bj][m][n]; ss += (x[0] * x[0] + x[1] * x[1]) + (x[2] * x[2] + x[3] * x[3]); }
;                     ss = row4_sum(ss);
;                     const float r = rsqrtf(ss * (1.f / 64.f) + EPS) * osc;
;                     bf16_t* rowp = base + (size_t)(row0 + ai * 128 + m * 16) * 512 + col0;
; #pragma unroll
;                     for (int bj = 0; bj < 2; ++bj) { const f32x4 v0 = acc[ai][bj][m][0] * r * g[bj][0], v1 = acc[ai][bj][m][1] * r * g[bj][1];
;                         u32x4 w; w.x = cvt_pk_bf16(v0[0], v0[1]); w.y = cvt_pk_bf16(v0[2], v0[3]); w.z = cvt_pk_bf16(v1[0], v1[1]); w.w = cvt_pk_bf16(v1[2], v1[3]);
;                         *(u32x4*)(rowp + 32 * bj) = w; }
;                 }
	v_add_f32_e32 v70, v70, v71
	v_mul_f32_e32 v71, v55, v55
	v_mul_f32_e32 v72, v57, v57
	v_fmac_f32_e32 v71, v54, v54
	v_fmac_f32_e32 v72, v56, v56
	v_add_f32_e32 v71, v71, v72
	v_add_f32_e32 v70, v70, v71
	v_mul_f32_e32 v71, v51, v51
	v_mul_f32_e32 v72, v53, v53
	v_fmac_f32_e32 v71, v50, v50
	v_fmac_f32_e32 v72, v52, v52
	v_add_f32_e32 v71, v71, v72
	v_add_f32_e32 v70, v70, v71
	v_mov_b32_e32 v71, v70
	s_nop 1
	v_permlane16_swap_b32_e32 v70, v71
	v_add_f32_e32 v70, v70, v71
	v_mov_b32_e32 v71, v70
	s_nop 1
	v_permlane32_swap_b32_e32 v70, v71
	v_add_f32_e32 v70, v70, v71
	v_fmamk_f32 v70, v70, 0x3c800000, v188
	v_mul_f32_e32 v71, 0x4b800000, v70
	v_cmp_gt_f32_e32 vcc, s91, v70
	v_cvt_pk_bf16_f32 v68, v68, v69
	v_cvt_pk_bf16_f32 v69, v74, v75
	global_store_dwordx4 v[84:85], v[66:69], off offset:64 sc1
	s_nop 0
	v_cndmask_b32_e32 v70, v70, v71, vcc
	v_rsq_f32_e32 v70, v70
	v_lshl_add_u64 v[68:69], v[174:175], 0, s[16:17]
	v_mul_f32_e32 v66, 0x45800000, v70
	v_cndmask_b32_e32 v66, v70, v66, vcc
	v_mul_f32_e32 v66, v178, v66
	v_pk_mul_f32 v[62:63], v[62:63], v[66:67] op_sel_hi:[1,0]
	v_pk_mul_f32 v[58:59], v[58:59], v[66:67] op_sel_hi:[1,0]
	v_pk_mul_f32 v[62:63], v[142:143], v[62:63]
	v_pk_mul_f32 v[60:61], v[60:61], v[66:67] op_sel_hi:[1,0]
	v_pk_mul_f32 v[64:65], v[64:65], v[66:67] op_sel_hi:[1,0]
	v_pk_mul_f32 v[70:71], v[140:141], v[60:61]
	v_pk_mul_f32 v[60:61], v[138:139], v[58:59]
	v_cvt_pk_bf16_f32 v58, v62, v63
	v_add_co_u32_e32 v62, vcc, s87, v174
	v_pk_mul_f32 v[54:55], v[54:55], v[66:67] op_sel_hi:[1,0]
	v_pk_mul_f32 v[64:65], v[144:145], v[64:65]
	v_addc_co_u32_e32 v63, vcc, 0, v175, vcc
	v_cvt_pk_bf16_f32 v59, v64, v65
	v_pk_mul_f32 v[54:55], v[134:135], v[54:55]
	v_pk_mul_f32 v[50:51], v[50:51], v[66:67] op_sel_hi:[1,0]
	v_pk_mul_f32 v[52:53], v[52:53], v[66:67] op_sel_hi:[1,0]
	v_cvt_pk_bf16_f32 v60, v60, v61
	v_cvt_pk_bf16_f32 v61, v70, v71
	global_store_dwordx4 v[62:63], v[58:61], off sc1
	v_pk_mul_f32 v[56:57], v[56:57], v[66:67] op_sel_hi:[1,0]
	s_nop 0
	v_pk_mul_f32 v[58:59], v[132:133], v[52:53]
	v_pk_mul_f32 v[52:53], v[130:131], v[50:51]
	v_cvt_pk_bf16_f32 v50, v54, v55
	v_mul_f32_e32 v54, v47, v47
	v_mul_f32_e32 v55, v49, v49
	v_pk_mul_f32 v[56:57], v[136:137], v[56:57]
	v_fmac_f32_e32 v54, v46, v46
	v_fmac_f32_e32 v55, v48, v48
	v_cvt_pk_bf16_f32 v51, v56, v57
	v_add_f32_e32 v54, v54, v55
	v_mul_f32_e32 v55, v43, v43
	v_mul_f32_e32 v56, v45, v45
	v_fmac_f32_e32 v55, v42, v42
	v_fmac_f32_e32 v56, v44, v44
	v_add_f32_e32 v55, v55, v56
	v_add_f32_e32 v54, v54, v55
	v_mul_f32_e32 v55, v39, v39
	v_mul_f32_e32 v56, v41, v41
	v_fmac_f32_e32 v55, v38, v38
	v_fmac_f32_e32 v56, v40, v40
	v_add_f32_e32 v55, v55, v56
	v_add_f32_e32 v54, v54, v55
	v_mul_f32_e32 v55, v35, v35
	v_mul_f32_e32 v56, v37, v37
	v_fmac_f32_e32 v55, v34, v34
	v_fmac_f32_e32 v56, v36, v36
	v_add_f32_e32 v55, v55, v56
	v_add_f32_e32 v54, v54, v55
	v_mov_b32_e32 v55, v54
	s_nop 1
	v_permlane16_swap_b32_e32 v54, v55
	v_add_f32_e32 v54, v54, v55
	v_mov_b32_e32 v55, v54
	s_nop 1
	v_permlane32_swap_b32_e32 v54, v55
	v_add_f32_e32 v54, v54, v55
	v_fmamk_f32 v54, v54, 0x3c800000, v188
	v_mul_f32_e32 v55, 0x4b800000, v54
	v_cmp_gt_f32_e32 vcc, s91, v54
	v_cvt_pk_bf16_f32 v52, v52, v53
	v_cvt_pk_bf16_f32 v53, v58, v59
	global_store_dwordx4 v[68:69], v[50:53], off offset:64 sc1
	s_nop 0
	v_cndmask_b32_e32 v54, v54, v55, vcc
	v_rsq_f32_e32 v54, v54
	v_lshl_add_u64 v[52:53], v[174:175], 0, s[18:19]
	v_mul_f32_e32 v50, 0x45800000, v54
	v_cndmask_b32_e32 v50, v54, v50, vcc
	v_mul_f32_e32 v50, v178, v50
	v_pk_mul_f32 v[46:47], v[46:47], v[50:51] op_sel_hi:[1,0]
	v_pk_mul_f32 v[42:43], v[42:43], v[50:51] op_sel_hi:[1,0]
	v_pk_mul_f32 v[46:47], v[142:143], v[46:47]
	v_pk_mul_f32 v[44:45], v[44:45], v[50:51] op_sel_hi:[1,0]
	v_pk_mul_f32 v[48:49], v[48:49], v[50:51] op_sel_hi:[1,0]
	v_pk_mul_f32 v[54:55], v[140:141], v[44:45]
	v_pk_mul_f32 v[44:45], v[138:139], v[42:43]
	v_cvt_pk_bf16_f32 v42, v46, v47
	v_add_co_u32_e32 v46, vcc, s88, v174
	v_pk_mul_f32 v[38:39], v[38:39], v[50:51] op_sel_hi:[1,0]
	v_pk_mul_f32 v[48:49], v[144:145], v[48:49]
	v_addc_co_u32_e32 v47, vcc, 0, v175, vcc
	v_cvt_pk_bf16_f32 v43, v48, v49
	v_pk_mul_f32 v[38:39], v[134:135], v[38:39]
	v_pk_mul_f32 v[34:35], v[34:35], v[50:51] op_sel_hi:[1,0]
	v_pk_mul_f32 v[36:37], v[36:37], v[50:51] op_sel_hi:[1,0]
	v_cvt_pk_bf16_f32 v44, v44, v45
	v_cvt_pk_bf16_f32 v45, v54, v55
	global_store_dwordx4 v[46:47], v[42:45], off sc1
	v_pk_mul_f32 v[40:41], v[40:41], v[50:51] op_sel_hi:[1,0]
	s_nop 0
	v_pk_mul_f32 v[42:43], v[132:133], v[36:37]
	v_pk_mul_f32 v[36:37], v[130:131], v[34:35]
	v_cvt_pk_bf16_f32 v34, v38, v39
	v_mul_f32_e32 v38, v31, v31
	v_mul_f32_e32 v39, v33, v33
	v_pk_mul_f32 v[40:41], v[136:137], v[40:41]
	v_fmac_f32_e32 v38, v30, v30
	v_fmac_f32_e32 v39, v32, v32
	v_cvt_pk_bf16_f32 v35, v40, v41
	v_add_f32_e32 v38, v38, v39
	v_mul_f32_e32 v39, v27, v27
	v_mul_f32_e32 v40, v29, v29
	v_fmac_f32_e32 v39, v26, v26
; __device__ __forceinline__ unsigned cvt_pk_bf16(float lo, float hi) { unsigned r; asm volatile("v_cvt_pk_bf16_f32 %0, %1, %2" : "=v"(r) : "v"(lo), "v"(hi)); return r; }
;     __device__ __forceinline__ void operator()(const f32x4 (&acc)[2][2][4][2], const pg8::Unit& u, int wr, int wc, int fr, int fq) const {
;     ...
;                 for (int m = 0; m < 4; ++m) {
;                     float ss = 0.f;
; #pragma unroll
;                     for (int bj = 0; bj < 2; ++bj)
; #pragma unroll
;                         for (int n = 0; n < 2; ++n) { const f32x4 x = acc[ai][bj][m][n]; ss += (x[0] * x[0] + x[1] * x[1]) + (x[2] * x[2] + x[3] * x[3]); }
;                     ss = row4_sum(ss);
;                     const float r = rsqrtf(ss * (1.f / 64.f) + EPS) * osc;
;                     bf16_t* rowp = base + (size_t)(row0 + ai * 128 + m * 16) * 512 + col0;
; #pragma unroll
;                     for (int bj = 0; bj < 2; ++bj) { const f32x4 v0 = acc[ai][bj][m][0] * r * g[bj][0], v1 = acc[ai][bj][m][1] * r * g[bj][1];
;                         u32x4 w; w.x = cvt_pk_bf16(v0[0], v0[1]); w.y = cvt_pk_bf16(v0[2], v0[3]); w.z = cvt_pk_bf16(v1[0], v1[1]); w.w = cvt_pk_bf16(v1[2], v1[3]);
;                         *(u32x4*)(rowp + 32 * bj) = w; }
;                 }
	v_fmac_f32_e32 v40, v28, v28
	v_add_f32_e32 v39, v39, v40
	v_add_f32_e32 v38, v38, v39
	v_mul_f32_e32 v39, v23, v23
	v_mul_f32_e32 v40, v25, v25
	v_fmac_f32_e32 v39, v22, v22
	v_fmac_f32_e32 v40, v24, v24
	v_add_f32_e32 v39, v39, v40
	v_add_f32_e32 v38, v38, v39
	v_mul_f32_e32 v39, v19, v19
	v_mul_f32_e32 v40, v21, v21
	v_fmac_f32_e32 v39, v18, v18
	v_fmac_f32_e32 v40, v20, v20
	v_add_f32_e32 v39, v39, v40
	v_add_f32_e32 v38, v38, v39
	v_mov_b32_e32 v39, v38
	s_nop 1
	v_permlane16_swap_b32_e32 v38, v39
	v_add_f32_e32 v38, v38, v39
	v_mov_b32_e32 v39, v38
	s_nop 1
	v_permlane32_swap_b32_e32 v38, v39
	v_add_f32_e32 v38, v38, v39
	v_fmamk_f32 v38, v38, 0x3c800000, v188
	v_mul_f32_e32 v39, 0x4b800000, v38
	v_cmp_gt_f32_e32 vcc, s91, v38
	v_cvt_pk_bf16_f32 v36, v36, v37
	v_cvt_pk_bf16_f32 v37, v42, v43
	global_store_dwordx4 v[52:53], v[34:37], off offset:64 sc1
	s_nop 0
	v_cndmask_b32_e32 v38, v38, v39, vcc
	v_rsq_f32_e32 v38, v38
	v_lshl_add_u64 v[36:37], v[174:175], 0, s[20:21]
	v_mul_f32_e32 v34, 0x45800000, v38
	v_cndmask_b32_e32 v34, v38, v34, vcc
	v_mul_f32_e32 v34, v178, v34
	v_pk_mul_f32 v[30:31], v[30:31], v[34:35] op_sel_hi:[1,0]
	v_pk_mul_f32 v[26:27], v[26:27], v[34:35] op_sel_hi:[1,0]
	v_pk_mul_f32 v[30:31], v[142:143], v[30:31]
	v_pk_mul_f32 v[28:29], v[28:29], v[34:35] op_sel_hi:[1,0]
	v_pk_mul_f32 v[32:33], v[32:33], v[34:35] op_sel_hi:[1,0]
	v_pk_mul_f32 v[38:39], v[140:141], v[28:29]
	v_pk_mul_f32 v[28:29], v[138:139], v[26:27]
	v_cvt_pk_bf16_f32 v26, v30, v31
	v_add_co_u32_e32 v30, vcc, s89, v174
	v_pk_mul_f32 v[22:23], v[22:23], v[34:35] op_sel_hi:[1,0]
	v_pk_mul_f32 v[32:33], v[144:145], v[32:33]
	v_addc_co_u32_e32 v31, vcc, 0, v175, vcc
	v_cvt_pk_bf16_f32 v27, v32, v33
	v_pk_mul_f32 v[22:23], v[134:135], v[22:23]
	v_pk_mul_f32 v[18:19], v[18:19], v[34:35] op_sel_hi:[1,0]
	v_pk_mul_f32 v[20:21], v[20:21], v[34:35] op_sel_hi:[1,0]
	v_cvt_pk_bf16_f32 v28, v28, v29
	v_cvt_pk_bf16_f32 v29, v38, v39
	global_store_dwordx4 v[30:31], v[26:29], off sc1
	v_pk_mul_f32 v[24:25], v[24:25], v[34:35] op_sel_hi:[1,0]
	s_nop 0
	v_pk_mul_f32 v[26:27], v[132:133], v[20:21]
	v_pk_mul_f32 v[20:21], v[130:131], v[18:19]
	v_cvt_pk_bf16_f32 v18, v22, v23
	v_mul_f32_e32 v22, v15, v15
	v_mul_f32_e32 v23, v17, v17
	v_pk_mul_f32 v[24:25], v[136:137], v[24:25]
	v_fmac_f32_e32 v22, v14, v14
	v_fmac_f32_e32 v23, v16, v16
	v_cvt_pk_bf16_f32 v19, v24, v25
	v_add_f32_e32 v22, v22, v23
	v_mul_f32_e32 v23, v11, v11
	v_mul_f32_e32 v24, v13, v13
	v_fmac_f32_e32 v23, v10, v10
	v_fmac_f32_e32 v24, v12, v12
	v_add_f32_e32 v23, v23, v24
	v_add_f32_e32 v22, v22, v23
	v_mul_f32_e32 v23, v7, v7
	v_mul_f32_e32 v24, v9, v9
	v_fmac_f32_e32 v23, v6, v6
	v_fmac_f32_e32 v24, v8, v8
	v_add_f32_e32 v23, v23, v24
	v_add_f32_e32 v22, v22, v23
	v_mul_f32_e32 v23, v3, v3
	v_mul_f32_e32 v24, v5, v5
	v_fmac_f32_e32 v23, v2, v2
	v_fmac_f32_e32 v24, v4, v4
	v_add_f32_e32 v23, v23, v24
	v_add_f32_e32 v22, v22, v23
	v_mov_b32_e32 v23, v22
	s_nop 1
	v_permlane16_swap_b32_e32 v22, v23
	v_add_f32_e32 v22, v22, v23
	v_mov_b32_e32 v23, v22
	s_nop 1
	v_permlane32_swap_b32_e32 v22, v23
	v_add_f32_e32 v22, v22, v23
	v_fmamk_f32 v22, v22, 0x3c800000, v188
	v_mul_f32_e32 v23, 0x4b800000, v22
	v_cmp_gt_f32_e32 vcc, s91, v22
	v_cvt_pk_bf16_f32 v20, v20, v21
	v_cvt_pk_bf16_f32 v21, v26, v27
	global_store_dwordx4 v[36:37], v[18:21], off offset:64 sc1
	s_nop 0
	v_cndmask_b32_e32 v22, v22, v23, vcc
	v_rsq_f32_e32 v22, v22
	v_lshl_add_u64 v[20:21], v[174:175], 0, s[24:25]
	v_mul_f32_e32 v18, 0x45800000, v22
	v_cndmask_b32_e32 v18, v22, v18, vcc
	v_mul_f32_e32 v18, v178, v18
	v_pk_mul_f32 v[14:15], v[14:15], v[18:19] op_sel_hi:[1,0]
	v_pk_mul_f32 v[10:11], v[10:11], v[18:19] op_sel_hi:[1,0]
	v_pk_mul_f32 v[14:15], v[142:143], v[14:15]
	v_pk_mul_f32 v[12:13], v[12:13], v[18:19] op_sel_hi:[1,0]
	v_pk_mul_f32 v[16:17], v[16:17], v[18:19] op_sel_hi:[1,0]
	v_pk_mul_f32 v[22:23], v[140:141], v[12:13]
	v_pk_mul_f32 v[12:13], v[138:139], v[10:11]
	v_cvt_pk_bf16_f32 v10, v14, v15
	v_add_co_u32_e32 v14, vcc, s90, v174
	v_pk_mul_f32 v[16:17], v[144:145], v[16:17]
	s_nop 0
	v_addc_co_u32_e32 v15, vcc, 0, v175, vcc
	v_cvt_pk_bf16_f32 v11, v16, v17
	v_pk_mul_f32 v[2:3], v[2:3], v[18:19] op_sel_hi:[1,0]
	v_pk_mul_f32 v[4:5], v[4:5], v[18:19] op_sel_hi:[1,0]
	v_cvt_pk_bf16_f32 v12, v12, v13
	v_cvt_pk_bf16_f32 v13, v22, v23
	global_store_dwordx4 v[14:15], v[10:13], off sc1
	v_pk_mul_f32 v[6:7], v[6:7], v[18:19] op_sel_hi:[1,0]
	v_pk_mul_f32 v[8:9], v[8:9], v[18:19] op_sel_hi:[1,0]
	v_pk_mul_f32 v[10:11], v[132:133], v[4:5]
	v_pk_mul_f32 v[4:5], v[130:131], v[2:3]
	v_pk_mul_f32 v[8:9], v[136:137], v[8:9]
	v_pk_mul_f32 v[6:7], v[134:135], v[6:7]
	s_nop 0
	v_cvt_pk_bf16_f32 v2, v6, v7
	v_cvt_pk_bf16_f32 v3, v8, v9
	v_cvt_pk_bf16_f32 v4, v4, v5
	v_cvt_pk_bf16_f32 v5, v10, v11
	global_store_dwordx4 v[20:21], v[2:5], off offset:64 sc1
	s_andn2_b64 vcc, exec, s[0:1]
	s_mov_b64 s[0:1], -1
	s_cbranch_vccnz .LBB0_158
